# conv (weight f32->bf16 transpose) and p-conversion loads marked nt
# speedup vs baseline: 1.0067x; 1.0039x over previous
.LBB0_15:
	s_mul_hi_i32 s0, s13, 0x10624dd3
	s_lshr_b32 s1, s0, 31
	s_ashr_i32 s0, s0, 3
	s_add_i32 s1, s0, s1
	s_lshl_b32 s0, s1, 6
	s_mulk_i32 s1, 0xf060
	s_add_i32 s6, s8, s1
	s_ashr_i32 s7, s6, 31
	v_or_b32_e32 v25, s0, v8
	v_lshl_add_u64 v[26:27], s[6:7], 2, v[2:3]
	v_or_b32_e32 v28, 8, v25
	v_or_b32_e32 v29, 16, v25
	v_or_b32_e32 v30, 24, v25
	v_or_b32_e32 v31, 32, v25
	v_or_b32_e32 v32, 40, v25
	v_or_b32_e32 v33, 48, v25
	v_or_b32_e32 v34, 56, v25
	v_mad_i64_i32 v[46:47], s[18:19], v25, s11, v[26:27]
	v_mad_i64_i32 v[62:63], s[18:19], v28, s11, v[26:27]
	v_mad_i64_i32 v[64:65], s[18:19], v29, s11, v[26:27]
	v_mad_i64_i32 v[66:67], s[18:19], v30, s11, v[26:27]
	v_mad_i64_i32 v[68:69], s[18:19], v31, s11, v[26:27]
	v_mad_i64_i32 v[70:71], s[18:19], v32, s11, v[26:27]
	v_mad_i64_i32 v[72:73], s[18:19], v33, s11, v[26:27]
	v_mad_i64_i32 v[74:75], s[18:19], v34, s11, v[26:27]
	global_load_dwordx4 v[26:29], v[46:47], off nt
	global_load_dwordx4 v[30:33], v[62:63], off nt
	global_load_dwordx4 v[34:37], v[64:65], off nt
	global_load_dwordx4 v[38:41], v[66:67], off nt
	global_load_dwordx4 v[42:45], v[68:69], off nt
	global_load_dwordx4 v[50:53], v[70:71], off nt
	global_load_dwordx4 v[54:57], v[72:73], off nt
	global_load_dwordx4 v[58:61], v[74:75], off nt
	v_add_u32_e32 v62, s6, v8
	s_ashr_i32 s1, s0, 31
	v_ashrrev_i32_e32 v63, 31, v62
	v_lshl_add_u64 v[46:47], s[0:1], 1, v[4:5]
	v_add_u32_e32 v64, 8, v62
	v_add_u32_e32 v66, 16, v62
	v_add_u32_e32 v68, 24, v62
	v_lshlrev_b64 v[62:63], 11, v[62:63]
	v_lshl_add_u64 v[62:63], v[46:47], 0, v[62:63]
	v_ashrrev_i32_e32 v65, 31, v64
	v_lshlrev_b64 v[64:65], 11, v[64:65]
	v_lshl_add_u64 v[64:65], v[46:47], 0, v[64:65]
	v_ashrrev_i32_e32 v67, 31, v66
	v_lshlrev_b64 v[66:67], 11, v[66:67]
	v_lshl_add_u64 v[66:67], v[46:47], 0, v[66:67]
	v_ashrrev_i32_e32 v69, 31, v68
	s_add_i32 s13, s13, s12
	s_add_i32 s8, s8, s9
	v_lshlrev_b64 v[68:69], 11, v[68:69]
	s_cmpk_lt_i32 s13, 0x7d0
	v_lshl_add_u64 v[46:47], v[46:47], 0, v[68:69]
	s_waitcnt vmcnt(0) lgkmcnt(0)
	ds_write2_b32 v10, v26, v27 offset1:1
	ds_write2_b32 v10, v28, v29 offset0:2 offset1:3
	ds_write2_b32 v11, v30, v31 offset1:1
	ds_write2_b32 v12, v32, v33 offset1:1
	ds_write2_b32 v13, v34, v35 offset1:1
	ds_write2_b32 v14, v36, v37 offset1:1
	ds_write2_b32 v15, v38, v39 offset1:1
	ds_write2_b32 v16, v40, v41 offset1:1
	ds_write2_b32 v17, v42, v43 offset1:1
	ds_write2_b32 v18, v44, v45 offset1:1
	ds_write2_b32 v19, v50, v51 offset1:1
	ds_write2_b32 v20, v52, v53 offset1:1
	ds_write2_b32 v21, v54, v55 offset1:1
	ds_write2_b32 v22, v56, v57 offset1:1
	ds_write2_b32 v23, v58, v59 offset1:1
	ds_write2_b32 v24, v60, v61 offset1:1
	ds_read_b32 v25, v9
	ds_read_b32 v26, v9 offset:132
	ds_read_b32 v27, v9 offset:264
	ds_read_b32 v28, v9 offset:396
	ds_read_b32 v29, v9 offset:528
	ds_read_b32 v30, v9 offset:660
	ds_read_b32 v31, v9 offset:792
	ds_read_b32 v32, v9 offset:924
	s_waitcnt lgkmcnt(6)
	v_cvt_pk_bf16_f32 v26, v25, v26
	s_waitcnt lgkmcnt(4)
	v_cvt_pk_bf16_f32 v27, v27, v28
	s_waitcnt lgkmcnt(2)
	v_cvt_pk_bf16_f32 v28, v29, v30
	s_waitcnt lgkmcnt(0)
	v_cvt_pk_bf16_f32 v29, v31, v32
	global_store_dwordx4 v[62:63], v[26:29], off
	ds_read_b32 v25, v9 offset:32
	ds_read_b32 v26, v9 offset:164
	ds_read_b32 v27, v9 offset:296
	ds_read_b32 v28, v9 offset:428
	ds_read_b32 v29, v9 offset:560
	ds_read_b32 v30, v9 offset:692
	ds_read_b32 v31, v9 offset:824
	ds_read_b32 v32, v9 offset:956
	s_waitcnt lgkmcnt(0)
	v_cvt_pk_bf16_f32 v26, v25, v26
	v_cvt_pk_bf16_f32 v27, v27, v28
	v_cvt_pk_bf16_f32 v28, v29, v30
	v_cvt_pk_bf16_f32 v29, v31, v32
	global_store_dwordx4 v[64:65], v[26:29], off
	ds_read_b32 v25, v9 offset:64
	ds_read_b32 v26, v9 offset:196
	ds_read_b32 v27, v9 offset:328
	ds_read_b32 v28, v9 offset:460
	ds_read_b32 v29, v9 offset:592
	ds_read_b32 v30, v9 offset:724
	ds_read_b32 v31, v9 offset:856
	ds_read_b32 v32, v9 offset:988
	s_waitcnt lgkmcnt(0)
	v_cvt_pk_bf16_f32 v26, v25, v26
	v_cvt_pk_bf16_f32 v27, v27, v28
	v_cvt_pk_bf16_f32 v28, v29, v30
	v_cvt_pk_bf16_f32 v29, v31, v32
	global_store_dwordx4 v[66:67], v[26:29], off
	ds_read_b32 v25, v9 offset:96
	ds_read_b32 v26, v9 offset:228
	ds_read_b32 v27, v9 offset:360
	ds_read_b32 v28, v9 offset:492
	ds_read_b32 v29, v9 offset:624
	ds_read_b32 v30, v9 offset:756
	ds_read_b32 v31, v9 offset:888
	ds_read_b32 v32, v9 offset:1020
	s_waitcnt lgkmcnt(0)
	v_cvt_pk_bf16_f32 v26, v25, v26
	v_cvt_pk_bf16_f32 v27, v27, v28
	v_cvt_pk_bf16_f32 v28, v29, v30
	v_cvt_pk_bf16_f32 v29, v31, v32
	global_store_dwordx4 v[46:47], v[26:29], off
	s_cbranch_scc1 .LBB0_15

.LBB0_18:
	s_ashr_i32 s4, s18, 31
	s_lshr_b32 s4, s4, 25
	s_add_i32 s4, s18, s4
	s_ashr_i32 s5, s4, 7
	s_lshl_b32 s4, s5, 6
	s_lshl_b32 s5, s5, 12
	s_sub_i32 s8, s11, s5
	s_ashr_i32 s9, s8, 31
	v_or_b32_e32 v25, s4, v8
	v_lshl_add_u64 v[26:27], s[8:9], 2, v[2:3]
	v_or_b32_e32 v28, 8, v25
	v_or_b32_e32 v29, 16, v25
	v_or_b32_e32 v30, 24, v25
	v_or_b32_e32 v31, 32, v25
	v_or_b32_e32 v32, 40, v25
	v_or_b32_e32 v33, 48, v25
	v_or_b32_e32 v34, 56, v25
	v_mad_i64_i32 v[46:47], s[20:21], v25, s17, v[26:27]
	v_mad_i64_i32 v[62:63], s[20:21], v28, s17, v[26:27]
	v_mad_i64_i32 v[64:65], s[20:21], v29, s17, v[26:27]
	v_mad_i64_i32 v[66:67], s[20:21], v30, s17, v[26:27]
	v_mad_i64_i32 v[68:69], s[20:21], v31, s17, v[26:27]
	v_mad_i64_i32 v[70:71], s[20:21], v32, s17, v[26:27]
	v_mad_i64_i32 v[72:73], s[20:21], v33, s17, v[26:27]
	v_mad_i64_i32 v[74:75], s[20:21], v34, s17, v[26:27]
	global_load_dwordx4 v[26:29], v[46:47], off nt
	global_load_dwordx4 v[30:33], v[62:63], off nt
	global_load_dwordx4 v[34:37], v[64:65], off nt
	global_load_dwordx4 v[38:41], v[66:67], off nt
	global_load_dwordx4 v[42:45], v[68:69], off nt
	global_load_dwordx4 v[50:53], v[70:71], off nt
	global_load_dwordx4 v[54:57], v[72:73], off nt
	global_load_dwordx4 v[58:61], v[74:75], off nt
	v_add_u32_e32 v62, s8, v8
	s_ashr_i32 s5, s4, 31
	v_ashrrev_i32_e32 v63, 31, v62
	v_lshl_add_u64 v[46:47], s[4:5], 1, v[4:5]
	v_add_u32_e32 v64, 8, v62
	v_add_u32_e32 v66, 16, v62
	v_add_u32_e32 v68, 24, v62
	v_lshlrev_b64 v[62:63], 11, v[62:63]
	v_lshl_add_u64 v[62:63], v[46:47], 0, v[62:63]
	v_ashrrev_i32_e32 v65, 31, v64
	v_lshlrev_b64 v[64:65], 11, v[64:65]
	v_lshl_add_u64 v[64:65], v[46:47], 0, v[64:65]
	v_ashrrev_i32_e32 v67, 31, v66
	v_lshlrev_b64 v[66:67], 11, v[66:67]
	v_lshl_add_u64 v[66:67], v[46:47], 0, v[66:67]
	v_ashrrev_i32_e32 v69, 31, v68
	s_add_i32 s18, s18, s12
	s_add_i32 s11, s11, s13
	v_lshlrev_b64 v[68:69], 11, v[68:69]
	s_cmpk_lt_i32 s18, 0x800
	v_lshl_add_u64 v[46:47], v[46:47], 0, v[68:69]
	s_waitcnt vmcnt(0) lgkmcnt(0)
	ds_write2_b32 v10, v26, v27 offset1:1
	ds_write2_b32 v10, v28, v29 offset0:2 offset1:3
	ds_write2_b32 v11, v30, v31 offset1:1
	ds_write2_b32 v12, v32, v33 offset1:1
	ds_write2_b32 v13, v34, v35 offset1:1
	ds_write2_b32 v14, v36, v37 offset1:1
	ds_write2_b32 v15, v38, v39 offset1:1
	ds_write2_b32 v16, v40, v41 offset1:1
	ds_write2_b32 v17, v42, v43 offset1:1
	ds_write2_b32 v18, v44, v45 offset1:1
	ds_write2_b32 v19, v50, v51 offset1:1
	ds_write2_b32 v20, v52, v53 offset1:1
	ds_write2_b32 v21, v54, v55 offset1:1
	ds_write2_b32 v22, v56, v57 offset1:1
	ds_write2_b32 v23, v58, v59 offset1:1
	ds_write2_b32 v24, v60, v61 offset1:1
	ds_read_b32 v25, v9
	ds_read_b32 v26, v9 offset:132
	ds_read_b32 v27, v9 offset:264
	ds_read_b32 v28, v9 offset:396
	ds_read_b32 v29, v9 offset:528
	ds_read_b32 v30, v9 offset:660
	ds_read_b32 v31, v9 offset:792
	ds_read_b32 v32, v9 offset:924
	s_waitcnt lgkmcnt(6)
	v_cvt_pk_bf16_f32 v26, v25, v26
	s_waitcnt lgkmcnt(4)
	v_cvt_pk_bf16_f32 v27, v27, v28
	s_waitcnt lgkmcnt(2)
	v_cvt_pk_bf16_f32 v28, v29, v30
	s_waitcnt lgkmcnt(0)
	v_cvt_pk_bf16_f32 v29, v31, v32
	global_store_dwordx4 v[62:63], v[26:29], off
	ds_read_b32 v25, v9 offset:32
	ds_read_b32 v26, v9 offset:164
	ds_read_b32 v27, v9 offset:296
	ds_read_b32 v28, v9 offset:428
	ds_read_b32 v29, v9 offset:560
	ds_read_b32 v30, v9 offset:692
	ds_read_b32 v31, v9 offset:824
	ds_read_b32 v32, v9 offset:956
	s_waitcnt lgkmcnt(0)
	v_cvt_pk_bf16_f32 v26, v25, v26
	v_cvt_pk_bf16_f32 v27, v27, v28
	v_cvt_pk_bf16_f32 v28, v29, v30
	v_cvt_pk_bf16_f32 v29, v31, v32
	global_store_dwordx4 v[64:65], v[26:29], off
	ds_read_b32 v25, v9 offset:64
	ds_read_b32 v26, v9 offset:196
	ds_read_b32 v27, v9 offset:328
	ds_read_b32 v28, v9 offset:460
	ds_read_b32 v29, v9 offset:592
	ds_read_b32 v30, v9 offset:724
	ds_read_b32 v31, v9 offset:856
	ds_read_b32 v32, v9 offset:988
	s_waitcnt lgkmcnt(0)
	v_cvt_pk_bf16_f32 v26, v25, v26
	v_cvt_pk_bf16_f32 v27, v27, v28
	v_cvt_pk_bf16_f32 v28, v29, v30
	v_cvt_pk_bf16_f32 v29, v31, v32
	global_store_dwordx4 v[66:67], v[26:29], off
	ds_read_b32 v25, v9 offset:96
	ds_read_b32 v26, v9 offset:228
	ds_read_b32 v27, v9 offset:360
	ds_read_b32 v28, v9 offset:492
	ds_read_b32 v29, v9 offset:624
	ds_read_b32 v30, v9 offset:756
	ds_read_b32 v31, v9 offset:888
	ds_read_b32 v32, v9 offset:1020
	s_waitcnt lgkmcnt(0)
	v_cvt_pk_bf16_f32 v26, v25, v26
	v_cvt_pk_bf16_f32 v27, v27, v28
	v_cvt_pk_bf16_f32 v28, v29, v30
	v_cvt_pk_bf16_f32 v29, v31, v32
	global_store_dwordx4 v[46:47], v[26:29], off
	s_cbranch_scc1 .LBB0_18

.LBB0_21:
	s_ashr_i32 s4, s11, 31
	s_lshr_b32 s4, s4, 25
	s_add_i32 s4, s11, s4
	s_ashr_i32 s5, s4, 7
	s_lshl_b32 s4, s5, 6
	s_lshl_b32 s5, s5, 12
	v_or_b32_e32 v26, s4, v8
	s_sub_i32 s6, s8, s5
	v_or_b32_e32 v28, 8, v26
	s_ashr_i32 s7, s6, 31
	v_ashrrev_i32_e32 v27, 31, v26
	v_or_b32_e32 v30, 16, v26
	v_or_b32_e32 v32, 24, v26
	v_or_b32_e32 v34, 32, v26
	v_or_b32_e32 v36, 40, v26
	v_or_b32_e32 v38, 48, v26
	v_or_b32_e32 v40, 56, v26
	v_ashrrev_i32_e32 v29, 31, v28
	v_lshl_add_u64 v[42:43], s[6:7], 2, v[2:3]
	v_lshlrev_b64 v[26:27], 14, v[26:27]
	v_ashrrev_i32_e32 v31, 31, v30
	v_ashrrev_i32_e32 v33, 31, v32
	v_ashrrev_i32_e32 v35, 31, v34
	v_ashrrev_i32_e32 v37, 31, v36
	v_ashrrev_i32_e32 v39, 31, v38
	v_ashrrev_i32_e32 v41, 31, v40
	v_lshlrev_b64 v[44:45], 14, v[28:29]
	v_lshl_add_u64 v[26:27], v[42:43], 0, v[26:27]
	v_lshlrev_b64 v[30:31], 14, v[30:31]
	v_lshlrev_b64 v[32:33], 14, v[32:33]
	v_lshlrev_b64 v[34:35], 14, v[34:35]
	v_lshlrev_b64 v[36:37], 14, v[36:37]
	v_lshlrev_b64 v[38:39], 14, v[38:39]
	v_lshlrev_b64 v[40:41], 14, v[40:41]
	v_lshl_add_u64 v[46:47], v[42:43], 0, v[44:45]
	global_load_dwordx4 v[26:29], v[26:27], off nt
	v_lshl_add_u64 v[62:63], v[42:43], 0, v[30:31]
	v_lshl_add_u64 v[64:65], v[42:43], 0, v[32:33]
	v_lshl_add_u64 v[66:67], v[42:43], 0, v[34:35]
	v_lshl_add_u64 v[68:69], v[42:43], 0, v[36:37]
	v_lshl_add_u64 v[70:71], v[42:43], 0, v[38:39]
	v_lshl_add_u64 v[72:73], v[42:43], 0, v[40:41]
	global_load_dwordx4 v[30:33], v[46:47], off nt
	global_load_dwordx4 v[34:37], v[62:63], off nt
	global_load_dwordx4 v[38:41], v[64:65], off nt
	global_load_dwordx4 v[42:45], v[66:67], off nt
	global_load_dwordx4 v[50:53], v[68:69], off nt
	global_load_dwordx4 v[54:57], v[70:71], off nt
	global_load_dwordx4 v[58:61], v[72:73], off nt
	v_add_u32_e32 v62, s6, v8
	s_ashr_i32 s5, s4, 31
	v_ashrrev_i32_e32 v63, 31, v62
	v_lshl_add_u64 v[46:47], s[4:5], 1, v[4:5]
	v_add_u32_e32 v64, 8, v62
	v_add_u32_e32 v66, 16, v62
	v_add_u32_e32 v68, 24, v62
	v_lshlrev_b64 v[62:63], 11, v[62:63]
	v_lshl_add_u64 v[62:63], v[46:47], 0, v[62:63]
	v_ashrrev_i32_e32 v65, 31, v64
	v_lshlrev_b64 v[64:65], 11, v[64:65]
	v_lshl_add_u64 v[64:65], v[46:47], 0, v[64:65]
	v_ashrrev_i32_e32 v67, 31, v66
	v_lshlrev_b64 v[66:67], 11, v[66:67]
	v_lshl_add_u64 v[66:67], v[46:47], 0, v[66:67]
	v_ashrrev_i32_e32 v69, 31, v68
	s_add_i32 s11, s11, s12
	s_add_i32 s8, s8, s9
	v_lshlrev_b64 v[68:69], 11, v[68:69]
	s_cmpk_lt_i32 s11, 0x800
	v_lshl_add_u64 v[46:47], v[46:47], 0, v[68:69]
	s_waitcnt vmcnt(0) lgkmcnt(0)
	ds_write2_b32 v10, v26, v27 offset1:1
	ds_write2_b32 v10, v28, v29 offset0:2 offset1:3
	ds_write2_b32 v11, v30, v31 offset1:1
	ds_write2_b32 v12, v32, v33 offset1:1
	ds_write2_b32 v13, v34, v35 offset1:1
	ds_write2_b32 v14, v36, v37 offset1:1
	ds_write2_b32 v15, v38, v39 offset1:1
	ds_write2_b32 v16, v40, v41 offset1:1
	ds_write2_b32 v17, v42, v43 offset1:1
	ds_write2_b32 v18, v44, v45 offset1:1
	ds_write2_b32 v19, v50, v51 offset1:1
	ds_write2_b32 v20, v52, v53 offset1:1
	ds_write2_b32 v21, v54, v55 offset1:1
	ds_write2_b32 v22, v56, v57 offset1:1
	ds_write2_b32 v23, v58, v59 offset1:1
	ds_write2_b32 v24, v60, v61 offset1:1
	ds_read_b32 v25, v9
	ds_read_b32 v26, v9 offset:132
	ds_read_b32 v27, v9 offset:264
	ds_read_b32 v28, v9 offset:396
	ds_read_b32 v29, v9 offset:528
	ds_read_b32 v30, v9 offset:660
	ds_read_b32 v31, v9 offset:792
	ds_read_b32 v32, v9 offset:924
	s_waitcnt lgkmcnt(6)
	v_cvt_pk_bf16_f32 v26, v25, v26
	s_waitcnt lgkmcnt(4)
	v_cvt_pk_bf16_f32 v27, v27, v28
	s_waitcnt lgkmcnt(2)
	v_cvt_pk_bf16_f32 v28, v29, v30
	s_waitcnt lgkmcnt(0)
	v_cvt_pk_bf16_f32 v29, v31, v32
	global_store_dwordx4 v[62:63], v[26:29], off
	ds_read_b32 v25, v9 offset:32
	ds_read_b32 v26, v9 offset:164
	ds_read_b32 v27, v9 offset:296
	ds_read_b32 v28, v9 offset:428
	ds_read_b32 v29, v9 offset:560
	ds_read_b32 v30, v9 offset:692
	ds_read_b32 v31, v9 offset:824
	ds_read_b32 v32, v9 offset:956
	s_waitcnt lgkmcnt(0)
	v_cvt_pk_bf16_f32 v26, v25, v26
	v_cvt_pk_bf16_f32 v27, v27, v28
	v_cvt_pk_bf16_f32 v28, v29, v30
	v_cvt_pk_bf16_f32 v29, v31, v32
	global_store_dwordx4 v[64:65], v[26:29], off
	ds_read_b32 v25, v9 offset:64
	ds_read_b32 v26, v9 offset:196
	ds_read_b32 v27, v9 offset:328
	ds_read_b32 v28, v9 offset:460
	ds_read_b32 v29, v9 offset:592
	ds_read_b32 v30, v9 offset:724
	ds_read_b32 v31, v9 offset:856
	ds_read_b32 v32, v9 offset:988
	s_waitcnt lgkmcnt(0)
	v_cvt_pk_bf16_f32 v26, v25, v26
	v_cvt_pk_bf16_f32 v27, v27, v28
	v_cvt_pk_bf16_f32 v28, v29, v30
	v_cvt_pk_bf16_f32 v29, v31, v32
	global_store_dwordx4 v[66:67], v[26:29], off
	ds_read_b32 v25, v9 offset:96
	ds_read_b32 v26, v9 offset:228
	ds_read_b32 v27, v9 offset:360
	ds_read_b32 v28, v9 offset:492
	ds_read_b32 v29, v9 offset:624
	ds_read_b32 v30, v9 offset:756
	ds_read_b32 v31, v9 offset:888
	ds_read_b32 v32, v9 offset:1020
	s_waitcnt lgkmcnt(0)
	v_cvt_pk_bf16_f32 v26, v25, v26
	v_cvt_pk_bf16_f32 v27, v27, v28
	v_cvt_pk_bf16_f32 v28, v29, v30
	v_cvt_pk_bf16_f32 v29, v31, v32
	global_store_dwordx4 v[46:47], v[26:29], off
	s_cbranch_scc1 .LBB0_21

.LBB0_26:
	s_ashr_i32 s0, s8, 31
	s_lshr_b32 s0, s0, 27
	s_add_i32 s0, s8, s0
	s_ashr_i32 s1, s0, 5
	s_lshl_b32 s0, s1, 6
	s_lshl_b32 s1, s1, 10
	v_or_b32_e32 v28, s0, v6
	s_sub_i32 s4, s6, s1
	v_or_b32_e32 v30, 8, v28
	s_ashr_i32 s5, s4, 31
	v_ashrrev_i32_e32 v29, 31, v28
	v_or_b32_e32 v32, 16, v28
	v_or_b32_e32 v34, 24, v28
	v_or_b32_e32 v36, 32, v28
	v_or_b32_e32 v38, 40, v28
	v_or_b32_e32 v44, 48, v28
	v_or_b32_e32 v46, 56, v28
	v_ashrrev_i32_e32 v31, 31, v30
	v_lshl_add_u64 v[52:53], s[4:5], 2, v[2:3]
	v_lshlrev_b64 v[28:29], 12, v[28:29]
	v_ashrrev_i32_e32 v33, 31, v32
	v_ashrrev_i32_e32 v35, 31, v34
	v_ashrrev_i32_e32 v37, 31, v36
	v_ashrrev_i32_e32 v39, 31, v38
	v_ashrrev_i32_e32 v45, 31, v44
	v_ashrrev_i32_e32 v47, 31, v46
	v_lshlrev_b64 v[54:55], 12, v[30:31]
	v_lshl_add_u64 v[28:29], v[52:53], 0, v[28:29]
	v_lshlrev_b64 v[32:33], 12, v[32:33]
	v_lshlrev_b64 v[34:35], 12, v[34:35]
	v_lshlrev_b64 v[36:37], 12, v[36:37]
	v_lshlrev_b64 v[38:39], 12, v[38:39]
	v_lshlrev_b64 v[44:45], 12, v[44:45]
	v_lshlrev_b64 v[46:47], 12, v[46:47]
	v_lshl_add_u64 v[68:69], v[52:53], 0, v[54:55]
	global_load_dwordx4 v[28:31], v[28:29], off nt
	v_lshl_add_u64 v[70:71], v[52:53], 0, v[32:33]
	v_lshl_add_u64 v[72:73], v[52:53], 0, v[34:35]
	v_lshl_add_u64 v[74:75], v[52:53], 0, v[36:37]
	v_lshl_add_u64 v[76:77], v[52:53], 0, v[38:39]
	v_lshl_add_u64 v[78:79], v[52:53], 0, v[44:45]
	v_lshl_add_u64 v[80:81], v[52:53], 0, v[46:47]
	global_load_dwordx4 v[32:35], v[68:69], off nt
	global_load_dwordx4 v[36:39], v[70:71], off nt
	global_load_dwordx4 v[44:47], v[72:73], off nt
	global_load_dwordx4 v[52:55], v[74:75], off nt
	global_load_dwordx4 v[56:59], v[76:77], off nt
	global_load_dwordx4 v[60:63], v[78:79], off nt
	global_load_dwordx4 v[64:67], v[80:81], off nt
	v_add_u32_e32 v70, s4, v6
	s_ashr_i32 s1, s0, 31
	v_ashrrev_i32_e32 v71, 31, v70
	v_lshl_add_u64 v[68:69], s[0:1], 1, v[4:5]
	v_add_u32_e32 v72, 8, v70
	v_add_u32_e32 v74, 16, v70
	v_add_u32_e32 v76, 24, v70
	v_lshlrev_b64 v[70:71], 13, v[70:71]
	v_lshl_add_u64 v[70:71], v[68:69], 0, v[70:71]
	v_ashrrev_i32_e32 v73, 31, v72
	v_lshlrev_b64 v[72:73], 13, v[72:73]
	v_lshl_add_u64 v[72:73], v[68:69], 0, v[72:73]
	v_ashrrev_i32_e32 v75, 31, v74
	v_lshlrev_b64 v[74:75], 13, v[74:75]
	v_lshl_add_u64 v[74:75], v[68:69], 0, v[74:75]
	v_ashrrev_i32_e32 v77, 31, v76
	s_add_i32 s8, s8, s12
	s_add_i32 s6, s6, s7
	v_lshlrev_b64 v[76:77], 13, v[76:77]
	s_cmpk_lt_i32 s8, 0x800
	v_lshl_add_u64 v[68:69], v[68:69], 0, v[76:77]
	s_waitcnt vmcnt(0) lgkmcnt(0)
	ds_write2_b32 v13, v28, v29 offset1:1
	ds_write2_b32 v13, v30, v31 offset0:2 offset1:3
	ds_write2_b32 v14, v32, v33 offset1:1
	ds_write2_b32 v15, v34, v35 offset1:1
	ds_write2_b32 v16, v36, v37 offset1:1
	ds_write2_b32 v17, v38, v39 offset1:1
	ds_write2_b32 v18, v44, v45 offset1:1
	ds_write2_b32 v19, v46, v47 offset1:1
	ds_write2_b32 v20, v52, v53 offset1:1
	ds_write2_b32 v21, v54, v55 offset1:1
	ds_write2_b32 v22, v56, v57 offset1:1
	ds_write2_b32 v23, v58, v59 offset1:1
	ds_write2_b32 v24, v60, v61 offset1:1
	ds_write2_b32 v25, v62, v63 offset1:1
	ds_write2_b32 v26, v64, v65 offset1:1
	ds_write2_b32 v27, v66, v67 offset1:1
	ds_read_b32 v28, v7
	ds_read_b32 v29, v7 offset:132
	ds_read_b32 v30, v7 offset:264
	ds_read_b32 v31, v7 offset:396
	ds_read_b32 v32, v7 offset:528
	ds_read_b32 v33, v7 offset:660
	ds_read_b32 v34, v7 offset:792
	ds_read_b32 v35, v7 offset:924
	s_waitcnt lgkmcnt(6)
	v_cvt_pk_bf16_f32 v28, v28, v29
	s_waitcnt lgkmcnt(4)
	v_cvt_pk_bf16_f32 v29, v30, v31
	s_waitcnt lgkmcnt(2)
	v_cvt_pk_bf16_f32 v30, v32, v33
	s_waitcnt lgkmcnt(0)
	v_cvt_pk_bf16_f32 v31, v34, v35
	global_store_dwordx4 v[70:71], v[28:31], off
	ds_read_b32 v28, v7 offset:32
	ds_read_b32 v29, v7 offset:164
	ds_read_b32 v30, v7 offset:296
	ds_read_b32 v31, v7 offset:428
	ds_read_b32 v32, v7 offset:560
	ds_read_b32 v33, v7 offset:692
	ds_read_b32 v34, v7 offset:824
	ds_read_b32 v35, v7 offset:956
	s_waitcnt lgkmcnt(0)
	v_cvt_pk_bf16_f32 v28, v28, v29
	v_cvt_pk_bf16_f32 v29, v30, v31
	v_cvt_pk_bf16_f32 v30, v32, v33
	v_cvt_pk_bf16_f32 v31, v34, v35
	global_store_dwordx4 v[72:73], v[28:31], off
	ds_read_b32 v28, v7 offset:64
	ds_read_b32 v29, v7 offset:196
	ds_read_b32 v30, v7 offset:328
	ds_read_b32 v31, v7 offset:460
	ds_read_b32 v32, v7 offset:592
	ds_read_b32 v33, v7 offset:724
	ds_read_b32 v34, v7 offset:856
	ds_read_b32 v35, v7 offset:988
	s_waitcnt lgkmcnt(0)
	v_cvt_pk_bf16_f32 v28, v28, v29
	v_cvt_pk_bf16_f32 v29, v30, v31
	v_cvt_pk_bf16_f32 v30, v32, v33
	v_cvt_pk_bf16_f32 v31, v34, v35
	global_store_dwordx4 v[74:75], v[28:31], off
	ds_read_b32 v28, v7 offset:96
	ds_read_b32 v29, v7 offset:228
	ds_read_b32 v30, v7 offset:360
	ds_read_b32 v31, v7 offset:492
	ds_read_b32 v32, v7 offset:624
	ds_read_b32 v33, v7 offset:756
	ds_read_b32 v34, v7 offset:888
	ds_read_b32 v35, v7 offset:1020
	s_waitcnt lgkmcnt(0)
	v_cvt_pk_bf16_f32 v28, v28, v29
	v_cvt_pk_bf16_f32 v29, v30, v31
	v_cvt_pk_bf16_f32 v30, v32, v33
	v_cvt_pk_bf16_f32 v31, v34, v35
	global_store_dwordx4 v[68:69], v[28:31], off
	s_cbranch_scc1 .LBB0_26
	v_mov_b32_e32 v38, v6

.LBB0_32:
	s_ashr_i32 s6, s17, 31
	s_lshr_b32 s6, s6, 27
	s_add_i32 s6, s17, s6
	s_ashr_i32 s6, s6, 5
	s_lshl_b32 s8, s6, 6
	s_lshl_b32 s6, s6, 10
	v_or_b32_e32 v20, s8, v38
	s_sub_i32 s6, s11, s6
	v_or_b32_e32 v22, 8, v20
	s_ashr_i32 s7, s6, 31
	v_ashrrev_i32_e32 v21, 31, v20
	v_or_b32_e32 v24, 16, v20
	v_or_b32_e32 v26, 24, v20
	v_or_b32_e32 v28, 32, v20
	v_or_b32_e32 v30, 40, v20
	v_or_b32_e32 v32, 48, v20
	v_or_b32_e32 v34, 56, v20
	v_ashrrev_i32_e32 v23, 31, v22
	v_lshl_add_u64 v[36:37], s[6:7], 2, v[6:7]
	v_lshlrev_b64 v[20:21], 12, v[20:21]
	v_ashrrev_i32_e32 v25, 31, v24
	v_ashrrev_i32_e32 v27, 31, v26
	v_ashrrev_i32_e32 v29, 31, v28
	v_ashrrev_i32_e32 v31, 31, v30
	v_ashrrev_i32_e32 v33, 31, v32
	v_ashrrev_i32_e32 v35, 31, v34
	v_lshlrev_b64 v[44:45], 12, v[22:23]
	v_lshl_add_u64 v[20:21], v[36:37], 0, v[20:21]
	v_lshlrev_b64 v[24:25], 12, v[24:25]
	v_lshlrev_b64 v[26:27], 12, v[26:27]
	v_lshlrev_b64 v[28:29], 12, v[28:29]
	v_lshlrev_b64 v[30:31], 12, v[30:31]
	v_lshlrev_b64 v[32:33], 12, v[32:33]
	v_lshlrev_b64 v[34:35], 12, v[34:35]
	v_lshl_add_u64 v[74:75], v[36:37], 0, v[44:45]
	global_load_dwordx4 v[20:23], v[20:21], off nt
	v_lshl_add_u64 v[76:77], v[36:37], 0, v[24:25]
	v_lshl_add_u64 v[78:79], v[36:37], 0, v[26:27]
	v_lshl_add_u64 v[80:81], v[36:37], 0, v[28:29]
	v_lshl_add_u64 v[82:83], v[36:37], 0, v[30:31]
	v_lshl_add_u64 v[84:85], v[36:37], 0, v[32:33]
	v_lshl_add_u64 v[36:37], v[36:37], 0, v[34:35]
	global_load_dwordx4 v[24:27], v[74:75], off nt
	global_load_dwordx4 v[28:31], v[76:77], off nt
	global_load_dwordx4 v[32:35], v[78:79], off nt
	global_load_dwordx4 v[44:47], v[80:81], off nt
	global_load_dwordx4 v[62:65], v[82:83], off nt
	global_load_dwordx4 v[66:69], v[84:85], off nt
	global_load_dwordx4 v[70:73], v[36:37], off nt
	v_add_u32_e32 v74, s6, v38
	s_ashr_i32 s9, s8, 31
	v_ashrrev_i32_e32 v75, 31, v74
	v_lshl_add_u64 v[36:37], s[8:9], 1, v[8:9]
	v_lshlrev_b64 v[74:75], 9, v[74:75]
	v_lshl_add_u64 v[74:75], v[36:37], 0, v[74:75]
	v_add_u32_e32 v76, s6, v49
	v_ashrrev_i32_e32 v77, 31, v76
	v_lshlrev_b64 v[76:77], 9, v[76:77]
	v_lshl_add_u64 v[76:77], v[36:37], 0, v[76:77]
	v_add_u32_e32 v78, s6, v50
	v_ashrrev_i32_e32 v79, 31, v78
	v_lshlrev_b64 v[78:79], 9, v[78:79]
	v_lshl_add_u64 v[78:79], v[36:37], 0, v[78:79]
	v_add_u32_e32 v80, s6, v51
	v_ashrrev_i32_e32 v81, 31, v80
	s_add_i32 s17, s17, s12
	s_add_i32 s11, s11, s13
	v_lshlrev_b64 v[80:81], 9, v[80:81]
	s_cmpk_lt_i32 s17, 0x80
	v_lshl_add_u64 v[36:37], v[36:37], 0, v[80:81]
	s_waitcnt vmcnt(0) lgkmcnt(0)
	ds_write2_b32 v56, v20, v21 offset1:1
	ds_write2_b32 v56, v22, v23 offset0:2 offset1:3
	ds_write2_b32 v57, v24, v25 offset1:1
	ds_write2_b32 v57, v26, v27 offset0:2 offset1:3
	ds_write2_b32 v58, v28, v29 offset1:1
	ds_write2_b32 v58, v30, v31 offset0:2 offset1:3
	ds_write2_b32 v59, v32, v33 offset1:1
	ds_write2_b32 v59, v34, v35 offset0:2 offset1:3
	ds_write2_b32 v10, v44, v45 offset1:1
	ds_write2_b32 v11, v46, v47 offset1:1
	ds_write2_b32 v13, v62, v63 offset1:1
	ds_write2_b32 v14, v64, v65 offset1:1
	ds_write2_b32 v15, v66, v67 offset1:1
	ds_write2_b32 v16, v68, v69 offset1:1
	ds_write2_b32 v17, v70, v71 offset1:1
	ds_write2_b32 v18, v72, v73 offset1:1
	ds_read2_b32 v[20:21], v52 offset1:33
	ds_read2_b32 v[22:23], v52 offset0:66 offset1:99
	ds_read2_b32 v[24:25], v52 offset0:132 offset1:165
	ds_read2_b32 v[26:27], v52 offset0:198 offset1:231
	s_waitcnt lgkmcnt(3)
	v_cvt_pk_bf16_f32 v20, v20, v21
	s_waitcnt lgkmcnt(2)
	v_cvt_pk_bf16_f32 v21, v22, v23
	s_waitcnt lgkmcnt(1)
	v_cvt_pk_bf16_f32 v22, v24, v25
	s_waitcnt lgkmcnt(0)
	v_cvt_pk_bf16_f32 v23, v26, v27
	global_store_dwordx4 v[74:75], v[20:23], off
	ds_read2_b32 v[20:21], v53 offset1:33
	ds_read2_b32 v[22:23], v53 offset0:66 offset1:99
	ds_read2_b32 v[24:25], v53 offset0:132 offset1:165
	ds_read2_b32 v[26:27], v53 offset0:198 offset1:231
	s_waitcnt lgkmcnt(0)
	v_cvt_pk_bf16_f32 v20, v20, v21
	v_cvt_pk_bf16_f32 v21, v22, v23
	v_cvt_pk_bf16_f32 v22, v24, v25
	v_cvt_pk_bf16_f32 v23, v26, v27
	global_store_dwordx4 v[76:77], v[20:23], off
	ds_read2_b32 v[20:21], v54 offset1:33
	ds_read2_b32 v[22:23], v54 offset0:66 offset1:99
	ds_read2_b32 v[24:25], v54 offset0:132 offset1:165
	ds_read2_b32 v[26:27], v54 offset0:198 offset1:231
	s_waitcnt lgkmcnt(0)
	v_cvt_pk_bf16_f32 v20, v20, v21
	v_cvt_pk_bf16_f32 v21, v22, v23
	v_cvt_pk_bf16_f32 v22, v24, v25
	v_cvt_pk_bf16_f32 v23, v26, v27
	global_store_dwordx4 v[78:79], v[20:23], off
	ds_read2_b32 v[20:21], v55 offset1:33
	ds_read2_b32 v[22:23], v55 offset0:66 offset1:99
	ds_read2_b32 v[24:25], v55 offset0:132 offset1:165
	ds_read2_b32 v[26:27], v55 offset0:198 offset1:231
	s_waitcnt lgkmcnt(0)
	v_cvt_pk_bf16_f32 v20, v20, v21
	v_cvt_pk_bf16_f32 v21, v22, v23
	v_cvt_pk_bf16_f32 v22, v24, v25
	v_cvt_pk_bf16_f32 v23, v26, v27
	global_store_dwordx4 v[36:37], v[20:23], off
	s_cbranch_scc1 .LBB0_32
	s_branch .LBB0_29

.LBB0_35:
	s_ashr_i32 s6, s11, 31
	s_lshr_b32 s6, s6, 27
	s_add_i32 s6, s11, s6
	s_ashr_i32 s6, s6, 5
	s_lshl_b32 s8, s6, 6
	s_lshl_b32 s6, s6, 10
	v_or_b32_e32 v16, s8, v38
	s_sub_i32 s6, s10, s6
	v_or_b32_e32 v18, 8, v16
	s_ashr_i32 s7, s6, 31
	v_ashrrev_i32_e32 v17, 31, v16
	v_or_b32_e32 v20, 16, v16
	v_or_b32_e32 v22, 24, v16
	v_or_b32_e32 v24, 32, v16
	v_or_b32_e32 v26, 40, v16
	v_or_b32_e32 v28, 48, v16
	v_or_b32_e32 v30, 56, v16
	v_ashrrev_i32_e32 v19, 31, v18
	v_lshl_add_u64 v[32:33], s[6:7], 2, v[4:5]
	v_lshlrev_b64 v[16:17], 12, v[16:17]
	v_ashrrev_i32_e32 v21, 31, v20
	v_ashrrev_i32_e32 v23, 31, v22
	v_ashrrev_i32_e32 v25, 31, v24
	v_ashrrev_i32_e32 v27, 31, v26
	v_ashrrev_i32_e32 v29, 31, v28
	v_ashrrev_i32_e32 v31, 31, v30
	v_lshlrev_b64 v[34:35], 12, v[18:19]
	v_lshl_add_u64 v[16:17], v[32:33], 0, v[16:17]
	v_lshlrev_b64 v[20:21], 12, v[20:21]
	v_lshlrev_b64 v[22:23], 12, v[22:23]
	v_lshlrev_b64 v[24:25], 12, v[24:25]
	v_lshlrev_b64 v[26:27], 12, v[26:27]
	v_lshlrev_b64 v[28:29], 12, v[28:29]
	v_lshlrev_b64 v[30:31], 12, v[30:31]
	v_lshl_add_u64 v[36:37], v[32:33], 0, v[34:35]
	global_load_dwordx4 v[16:19], v[16:17], off nt
	v_lshl_add_u64 v[70:71], v[32:33], 0, v[20:21]
	v_lshl_add_u64 v[72:73], v[32:33], 0, v[22:23]
	v_lshl_add_u64 v[74:75], v[32:33], 0, v[24:25]
	v_lshl_add_u64 v[76:77], v[32:33], 0, v[26:27]
	v_lshl_add_u64 v[78:79], v[32:33], 0, v[28:29]
	v_lshl_add_u64 v[80:81], v[32:33], 0, v[30:31]
	global_load_dwordx4 v[20:23], v[36:37], off nt
	global_load_dwordx4 v[24:27], v[70:71], off nt
	global_load_dwordx4 v[28:31], v[72:73], off nt
	global_load_dwordx4 v[32:35], v[74:75], off nt
	global_load_dwordx4 v[44:47], v[76:77], off nt
	global_load_dwordx4 v[62:65], v[78:79], off nt
	global_load_dwordx4 v[66:69], v[80:81], off nt
	v_add_u32_e32 v70, s6, v38
	s_ashr_i32 s9, s8, 31
	v_ashrrev_i32_e32 v71, 31, v70
	v_lshl_add_u64 v[36:37], s[8:9], 1, v[6:7]
	v_lshlrev_b64 v[70:71], 11, v[70:71]
	v_lshl_add_u64 v[70:71], v[36:37], 0, v[70:71]
	v_add_u32_e32 v72, s6, v49
	v_ashrrev_i32_e32 v73, 31, v72
	v_lshlrev_b64 v[72:73], 11, v[72:73]
	v_lshl_add_u64 v[72:73], v[36:37], 0, v[72:73]
	v_add_u32_e32 v74, s6, v50
	v_ashrrev_i32_e32 v75, 31, v74
	v_lshlrev_b64 v[74:75], 11, v[74:75]
	v_lshl_add_u64 v[74:75], v[36:37], 0, v[74:75]
	v_add_u32_e32 v76, s6, v51
	v_ashrrev_i32_e32 v77, 31, v76
	s_add_i32 s11, s11, s12
	s_add_i32 s10, s10, s13
	v_lshlrev_b64 v[76:77], 11, v[76:77]
	s_cmpk_lt_i32 s11, 0x200
	v_lshl_add_u64 v[36:37], v[36:37], 0, v[76:77]
	s_waitcnt vmcnt(0) lgkmcnt(0)
	ds_write2_b32 v56, v16, v17 offset1:1
	ds_write2_b32 v56, v18, v19 offset0:2 offset1:3
	ds_write2_b32 v57, v20, v21 offset1:1
	ds_write2_b32 v57, v22, v23 offset0:2 offset1:3
	ds_write2_b32 v58, v24, v25 offset1:1
	ds_write2_b32 v58, v26, v27 offset0:2 offset1:3
	ds_write2_b32 v59, v28, v29 offset1:1
	ds_write2_b32 v59, v30, v31 offset0:2 offset1:3
	ds_write2_b32 v8, v32, v33 offset1:1
	ds_write2_b32 v9, v34, v35 offset1:1
	ds_write2_b32 v10, v44, v45 offset1:1
	ds_write2_b32 v11, v46, v47 offset1:1
	ds_write2_b32 v12, v62, v63 offset1:1
	ds_write2_b32 v13, v64, v65 offset1:1
	ds_write2_b32 v14, v66, v67 offset1:1
	ds_write2_b32 v15, v68, v69 offset1:1
	ds_read2_b32 v[16:17], v52 offset1:33
	ds_read2_b32 v[18:19], v52 offset0:66 offset1:99
	ds_read2_b32 v[20:21], v52 offset0:132 offset1:165
	ds_read2_b32 v[22:23], v52 offset0:198 offset1:231
	s_waitcnt lgkmcnt(3)
	v_cvt_pk_bf16_f32 v16, v16, v17
	s_waitcnt lgkmcnt(2)
	v_cvt_pk_bf16_f32 v17, v18, v19
	s_waitcnt lgkmcnt(1)
	v_cvt_pk_bf16_f32 v18, v20, v21
	s_waitcnt lgkmcnt(0)
	v_cvt_pk_bf16_f32 v19, v22, v23
	global_store_dwordx4 v[70:71], v[16:19], off
	ds_read2_b32 v[16:17], v53 offset1:33
	ds_read2_b32 v[18:19], v53 offset0:66 offset1:99
	ds_read2_b32 v[20:21], v53 offset0:132 offset1:165
	ds_read2_b32 v[22:23], v53 offset0:198 offset1:231
	s_waitcnt lgkmcnt(0)
	v_cvt_pk_bf16_f32 v16, v16, v17
	v_cvt_pk_bf16_f32 v17, v18, v19
	v_cvt_pk_bf16_f32 v18, v20, v21
	v_cvt_pk_bf16_f32 v19, v22, v23
	global_store_dwordx4 v[72:73], v[16:19], off
	ds_read2_b32 v[16:17], v54 offset1:33
	ds_read2_b32 v[18:19], v54 offset0:66 offset1:99
	ds_read2_b32 v[20:21], v54 offset0:132 offset1:165
	ds_read2_b32 v[22:23], v54 offset0:198 offset1:231
	s_waitcnt lgkmcnt(0)
	v_cvt_pk_bf16_f32 v16, v16, v17
	v_cvt_pk_bf16_f32 v17, v18, v19
	v_cvt_pk_bf16_f32 v18, v20, v21
	v_cvt_pk_bf16_f32 v19, v22, v23
	global_store_dwordx4 v[74:75], v[16:19], off
	ds_read2_b32 v[16:17], v55 offset1:33
	ds_read2_b32 v[18:19], v55 offset0:66 offset1:99
	ds_read2_b32 v[20:21], v55 offset0:132 offset1:165
	ds_read2_b32 v[22:23], v55 offset0:198 offset1:231
	s_waitcnt lgkmcnt(0)
	v_cvt_pk_bf16_f32 v16, v16, v17
	v_cvt_pk_bf16_f32 v17, v18, v19
	v_cvt_pk_bf16_f32 v18, v20, v21
	v_cvt_pk_bf16_f32 v19, v22, v23
	global_store_dwordx4 v[36:37], v[16:19], off
	s_cbranch_scc1 .LBB0_35

.LBB0_38:
	s_ashr_i32 s4, s9, 31
	s_lshr_b32 s4, s4, 27
	s_add_i32 s4, s9, s4
	s_ashr_i32 s4, s4, 5
	s_lshl_b32 s6, s4, 6
	s_lshl_b32 s4, s4, 10
	v_or_b32_e32 v16, s6, v38
	s_sub_i32 s4, s8, s4
	v_or_b32_e32 v18, 8, v16
	s_ashr_i32 s5, s4, 31
	v_ashrrev_i32_e32 v17, 31, v16
	v_or_b32_e32 v20, 16, v16
	v_or_b32_e32 v22, 24, v16
	v_or_b32_e32 v24, 32, v16
	v_or_b32_e32 v26, 40, v16
	v_or_b32_e32 v28, 48, v16
	v_or_b32_e32 v30, 56, v16
	v_ashrrev_i32_e32 v19, 31, v18
	v_lshl_add_u64 v[32:33], s[4:5], 2, v[4:5]
	v_lshlrev_b64 v[16:17], 12, v[16:17]
	v_ashrrev_i32_e32 v21, 31, v20
	v_ashrrev_i32_e32 v23, 31, v22
	v_ashrrev_i32_e32 v25, 31, v24
	v_ashrrev_i32_e32 v27, 31, v26
	v_ashrrev_i32_e32 v29, 31, v28
	v_ashrrev_i32_e32 v31, 31, v30
	v_lshlrev_b64 v[34:35], 12, v[18:19]
	v_lshl_add_u64 v[16:17], v[32:33], 0, v[16:17]
	v_lshlrev_b64 v[20:21], 12, v[20:21]
	v_lshlrev_b64 v[22:23], 12, v[22:23]
	v_lshlrev_b64 v[24:25], 12, v[24:25]
	v_lshlrev_b64 v[26:27], 12, v[26:27]
	v_lshlrev_b64 v[28:29], 12, v[28:29]
	v_lshlrev_b64 v[30:31], 12, v[30:31]
	v_lshl_add_u64 v[36:37], v[32:33], 0, v[34:35]
	global_load_dwordx4 v[16:19], v[16:17], off nt
	v_lshl_add_u64 v[70:71], v[32:33], 0, v[20:21]
	v_lshl_add_u64 v[72:73], v[32:33], 0, v[22:23]
	v_lshl_add_u64 v[74:75], v[32:33], 0, v[24:25]
	v_lshl_add_u64 v[76:77], v[32:33], 0, v[26:27]
	v_lshl_add_u64 v[78:79], v[32:33], 0, v[28:29]
	v_lshl_add_u64 v[80:81], v[32:33], 0, v[30:31]
	global_load_dwordx4 v[20:23], v[36:37], off nt
	global_load_dwordx4 v[24:27], v[70:71], off nt
	global_load_dwordx4 v[28:31], v[72:73], off nt
	global_load_dwordx4 v[32:35], v[74:75], off nt
	global_load_dwordx4 v[44:47], v[76:77], off nt
	global_load_dwordx4 v[62:65], v[78:79], off nt
	global_load_dwordx4 v[66:69], v[80:81], off nt
	v_add_u32_e32 v70, s4, v38
	s_ashr_i32 s7, s6, 31
	v_ashrrev_i32_e32 v71, 31, v70
	v_lshl_add_u64 v[36:37], s[6:7], 1, v[6:7]
	v_lshlrev_b64 v[70:71], 11, v[70:71]
	v_lshl_add_u64 v[70:71], v[36:37], 0, v[70:71]
	v_add_u32_e32 v72, s4, v49
	v_ashrrev_i32_e32 v73, 31, v72
	v_lshlrev_b64 v[72:73], 11, v[72:73]
	v_lshl_add_u64 v[72:73], v[36:37], 0, v[72:73]
	v_add_u32_e32 v74, s4, v50
	v_ashrrev_i32_e32 v75, 31, v74
	v_lshlrev_b64 v[74:75], 11, v[74:75]
	v_lshl_add_u64 v[74:75], v[36:37], 0, v[74:75]
	v_add_u32_e32 v76, s4, v51
	v_ashrrev_i32_e32 v77, 31, v76
	s_add_i32 s9, s9, s12
	s_add_i32 s8, s8, s13
	v_lshlrev_b64 v[76:77], 11, v[76:77]
	s_cmpk_lt_i32 s9, 0x200
	v_lshl_add_u64 v[36:37], v[36:37], 0, v[76:77]
	s_waitcnt vmcnt(0) lgkmcnt(0)
	ds_write2_b32 v56, v16, v17 offset1:1
	ds_write2_b32 v56, v18, v19 offset0:2 offset1:3
	ds_write2_b32 v57, v20, v21 offset1:1
	ds_write2_b32 v57, v22, v23 offset0:2 offset1:3
	ds_write2_b32 v58, v24, v25 offset1:1
	ds_write2_b32 v58, v26, v27 offset0:2 offset1:3
	ds_write2_b32 v59, v28, v29 offset1:1
	ds_write2_b32 v59, v30, v31 offset0:2 offset1:3
	ds_write2_b32 v8, v32, v33 offset1:1
	ds_write2_b32 v9, v34, v35 offset1:1
	ds_write2_b32 v10, v44, v45 offset1:1
	ds_write2_b32 v11, v46, v47 offset1:1
	ds_write2_b32 v12, v62, v63 offset1:1
	ds_write2_b32 v13, v64, v65 offset1:1
	ds_write2_b32 v14, v66, v67 offset1:1
	ds_write2_b32 v15, v68, v69 offset1:1
	ds_read2_b32 v[16:17], v52 offset1:33
	ds_read2_b32 v[18:19], v52 offset0:66 offset1:99
	ds_read2_b32 v[20:21], v52 offset0:132 offset1:165
	ds_read2_b32 v[22:23], v52 offset0:198 offset1:231
	s_waitcnt lgkmcnt(3)
	v_cvt_pk_bf16_f32 v16, v16, v17
	s_waitcnt lgkmcnt(2)
	v_cvt_pk_bf16_f32 v17, v18, v19
	s_waitcnt lgkmcnt(1)
	v_cvt_pk_bf16_f32 v18, v20, v21
	s_waitcnt lgkmcnt(0)
	v_cvt_pk_bf16_f32 v19, v22, v23
	global_store_dwordx4 v[70:71], v[16:19], off
	ds_read2_b32 v[16:17], v53 offset1:33
	ds_read2_b32 v[18:19], v53 offset0:66 offset1:99
	ds_read2_b32 v[20:21], v53 offset0:132 offset1:165
	ds_read2_b32 v[22:23], v53 offset0:198 offset1:231
	s_waitcnt lgkmcnt(0)
	v_cvt_pk_bf16_f32 v16, v16, v17
	v_cvt_pk_bf16_f32 v17, v18, v19
	v_cvt_pk_bf16_f32 v18, v20, v21
	v_cvt_pk_bf16_f32 v19, v22, v23
	global_store_dwordx4 v[72:73], v[16:19], off
	ds_read2_b32 v[16:17], v54 offset1:33
	ds_read2_b32 v[18:19], v54 offset0:66 offset1:99
	ds_read2_b32 v[20:21], v54 offset0:132 offset1:165
	ds_read2_b32 v[22:23], v54 offset0:198 offset1:231
	s_waitcnt lgkmcnt(0)
	v_cvt_pk_bf16_f32 v16, v16, v17
	v_cvt_pk_bf16_f32 v17, v18, v19
	v_cvt_pk_bf16_f32 v18, v20, v21
	v_cvt_pk_bf16_f32 v19, v22, v23
	global_store_dwordx4 v[74:75], v[16:19], off
	ds_read2_b32 v[16:17], v55 offset1:33
	ds_read2_b32 v[18:19], v55 offset0:66 offset1:99
	ds_read2_b32 v[20:21], v55 offset0:132 offset1:165
	ds_read2_b32 v[22:23], v55 offset0:198 offset1:231
	s_waitcnt lgkmcnt(0)
	v_cvt_pk_bf16_f32 v16, v16, v17
	v_cvt_pk_bf16_f32 v17, v18, v19
	v_cvt_pk_bf16_f32 v18, v20, v21
	v_cvt_pk_bf16_f32 v19, v22, v23
	global_store_dwordx4 v[36:37], v[16:19], off
	s_cbranch_scc1 .LBB0_38

.LBB0_41:
	s_ashr_i32 s0, s7, 31
	s_lshr_b32 s0, s0, 27
	s_add_i32 s0, s7, s0
	s_ashr_i32 s0, s0, 5
	s_lshl_b32 s4, s0, 6
	s_lshl_b32 s0, s0, 10
	v_or_b32_e32 v16, s4, v38
	s_sub_i32 s0, s6, s0
	v_or_b32_e32 v18, 8, v16
	s_ashr_i32 s1, s0, 31
	v_ashrrev_i32_e32 v17, 31, v16
	v_or_b32_e32 v20, 16, v16
	v_or_b32_e32 v22, 24, v16
	v_or_b32_e32 v24, 32, v16
	v_or_b32_e32 v26, 40, v16
	v_or_b32_e32 v28, 48, v16
	v_or_b32_e32 v30, 56, v16
	v_ashrrev_i32_e32 v19, 31, v18
	v_lshl_add_u64 v[32:33], s[0:1], 2, v[4:5]
	v_lshlrev_b64 v[16:17], 12, v[16:17]
	v_ashrrev_i32_e32 v21, 31, v20
	v_ashrrev_i32_e32 v23, 31, v22
	v_ashrrev_i32_e32 v25, 31, v24
	v_ashrrev_i32_e32 v27, 31, v26
	v_ashrrev_i32_e32 v29, 31, v28
	v_ashrrev_i32_e32 v31, 31, v30
	v_lshlrev_b64 v[34:35], 12, v[18:19]
	v_lshl_add_u64 v[16:17], v[32:33], 0, v[16:17]
	v_lshlrev_b64 v[20:21], 12, v[20:21]
	v_lshlrev_b64 v[22:23], 12, v[22:23]
	v_lshlrev_b64 v[24:25], 12, v[24:25]
	v_lshlrev_b64 v[26:27], 12, v[26:27]
	v_lshlrev_b64 v[28:29], 12, v[28:29]
	v_lshlrev_b64 v[30:31], 12, v[30:31]
	v_lshl_add_u64 v[36:37], v[32:33], 0, v[34:35]
	global_load_dwordx4 v[16:19], v[16:17], off nt
	v_lshl_add_u64 v[70:71], v[32:33], 0, v[20:21]
	v_lshl_add_u64 v[72:73], v[32:33], 0, v[22:23]
	v_lshl_add_u64 v[74:75], v[32:33], 0, v[24:25]
	v_lshl_add_u64 v[76:77], v[32:33], 0, v[26:27]
	v_lshl_add_u64 v[78:79], v[32:33], 0, v[28:29]
	v_lshl_add_u64 v[80:81], v[32:33], 0, v[30:31]
	global_load_dwordx4 v[20:23], v[36:37], off nt
	global_load_dwordx4 v[24:27], v[70:71], off nt
	global_load_dwordx4 v[28:31], v[72:73], off nt
	global_load_dwordx4 v[32:35], v[74:75], off nt
	global_load_dwordx4 v[44:47], v[76:77], off nt
	global_load_dwordx4 v[62:65], v[78:79], off nt
	global_load_dwordx4 v[66:69], v[80:81], off nt
	v_add_u32_e32 v70, s0, v38
	s_ashr_i32 s5, s4, 31
	v_ashrrev_i32_e32 v71, 31, v70
	v_lshl_add_u64 v[36:37], s[4:5], 1, v[6:7]
	v_lshlrev_b64 v[70:71], 9, v[70:71]
	v_lshl_add_u64 v[70:71], v[36:37], 0, v[70:71]
	v_add_u32_e32 v72, s0, v49
	v_ashrrev_i32_e32 v73, 31, v72
	v_lshlrev_b64 v[72:73], 9, v[72:73]
	v_lshl_add_u64 v[72:73], v[36:37], 0, v[72:73]
	v_add_u32_e32 v74, s0, v50
	v_ashrrev_i32_e32 v75, 31, v74
	v_lshlrev_b64 v[74:75], 9, v[74:75]
	v_lshl_add_u64 v[74:75], v[36:37], 0, v[74:75]
	v_add_u32_e32 v76, s0, v51
	v_ashrrev_i32_e32 v77, 31, v76
	s_add_i32 s7, s7, s12
	s_add_i32 s6, s6, s13
	v_lshlrev_b64 v[76:77], 9, v[76:77]
	s_cmpk_lt_i32 s7, 0x80
	v_lshl_add_u64 v[36:37], v[36:37], 0, v[76:77]
	s_waitcnt vmcnt(0) lgkmcnt(0)
	ds_write2_b32 v56, v16, v17 offset1:1
	ds_write2_b32 v56, v18, v19 offset0:2 offset1:3
	ds_write2_b32 v57, v20, v21 offset1:1
	ds_write2_b32 v57, v22, v23 offset0:2 offset1:3
	ds_write2_b32 v58, v24, v25 offset1:1
	ds_write2_b32 v58, v26, v27 offset0:2 offset1:3
	ds_write2_b32 v59, v28, v29 offset1:1
	ds_write2_b32 v59, v30, v31 offset0:2 offset1:3
	ds_write2_b32 v8, v32, v33 offset1:1
	ds_write2_b32 v9, v34, v35 offset1:1
	ds_write2_b32 v10, v44, v45 offset1:1
	ds_write2_b32 v11, v46, v47 offset1:1
	ds_write2_b32 v12, v62, v63 offset1:1
	ds_write2_b32 v13, v64, v65 offset1:1
	ds_write2_b32 v14, v66, v67 offset1:1
	ds_write2_b32 v15, v68, v69 offset1:1
	ds_read2_b32 v[16:17], v52 offset1:33
	ds_read2_b32 v[18:19], v52 offset0:66 offset1:99
	ds_read2_b32 v[20:21], v52 offset0:132 offset1:165
	ds_read2_b32 v[22:23], v52 offset0:198 offset1:231
	s_waitcnt lgkmcnt(3)
	v_cvt_pk_bf16_f32 v16, v16, v17
	s_waitcnt lgkmcnt(2)
	v_cvt_pk_bf16_f32 v17, v18, v19
	s_waitcnt lgkmcnt(1)
	v_cvt_pk_bf16_f32 v18, v20, v21
	s_waitcnt lgkmcnt(0)
	v_cvt_pk_bf16_f32 v19, v22, v23
	global_store_dwordx4 v[70:71], v[16:19], off
	ds_read2_b32 v[16:17], v53 offset1:33
	ds_read2_b32 v[18:19], v53 offset0:66 offset1:99
	ds_read2_b32 v[20:21], v53 offset0:132 offset1:165
	ds_read2_b32 v[22:23], v53 offset0:198 offset1:231
	s_waitcnt lgkmcnt(0)
	v_cvt_pk_bf16_f32 v16, v16, v17
	v_cvt_pk_bf16_f32 v17, v18, v19
	v_cvt_pk_bf16_f32 v18, v20, v21
	v_cvt_pk_bf16_f32 v19, v22, v23
	global_store_dwordx4 v[72:73], v[16:19], off
	ds_read2_b32 v[16:17], v54 offset1:33
	ds_read2_b32 v[18:19], v54 offset0:66 offset1:99
	ds_read2_b32 v[20:21], v54 offset0:132 offset1:165
	ds_read2_b32 v[22:23], v54 offset0:198 offset1:231
	s_waitcnt lgkmcnt(0)
	v_cvt_pk_bf16_f32 v16, v16, v17
	v_cvt_pk_bf16_f32 v17, v18, v19
	v_cvt_pk_bf16_f32 v18, v20, v21
	v_cvt_pk_bf16_f32 v19, v22, v23
	global_store_dwordx4 v[74:75], v[16:19], off
	ds_read2_b32 v[16:17], v55 offset1:33
	ds_read2_b32 v[18:19], v55 offset0:66 offset1:99
	ds_read2_b32 v[20:21], v55 offset0:132 offset1:165
	ds_read2_b32 v[22:23], v55 offset0:198 offset1:231
	s_waitcnt lgkmcnt(0)
	v_cvt_pk_bf16_f32 v16, v16, v17
	v_cvt_pk_bf16_f32 v17, v18, v19
	v_cvt_pk_bf16_f32 v18, v20, v21
	v_cvt_pk_bf16_f32 v19, v22, v23
	global_store_dwordx4 v[36:37], v[16:19], off
	s_cbranch_scc1 .LBB0_41

.LBB0_45:
	s_mul_hi_i32 s6, s19, 0x2aaaaaab
	s_lshr_b32 s7, s6, 31
	s_ashr_i32 s6, s6, 1
	s_add_i32 s6, s6, s7
	s_lshl_b32 s8, s6, 6
	s_mulk_i32 s6, 0xfe80
	s_add_i32 s6, s17, s6
	s_ashr_i32 s7, s6, 31
	v_or_b32_e32 v34, s8, v38
	v_lshl_add_u64 v[2:3], s[6:7], 2, v[44:45]
	v_mad_i64_i32 v[4:5], s[10:11], v34, s18, v[2:3]
	v_or_b32_e32 v6, 8, v34
	v_mad_i64_i32 v[6:7], s[10:11], v6, s18, v[2:3]
	global_load_dwordx4 v[26:29], v[4:5], off nt
	global_load_dwordx4 v[30:33], v[6:7], off nt
	v_or_b32_e32 v4, 16, v34
	v_mad_i64_i32 v[4:5], s[10:11], v4, s18, v[2:3]
	v_or_b32_e32 v6, 24, v34
	v_mad_i64_i32 v[6:7], s[10:11], v6, s18, v[2:3]
	global_load_dwordx4 v[18:21], v[4:5], off nt
	global_load_dwordx4 v[22:25], v[6:7], off nt
	v_or_b32_e32 v4, 32, v34
	v_mad_i64_i32 v[4:5], s[10:11], v4, s18, v[2:3]
	v_or_b32_e32 v6, 40, v34
	v_mad_i64_i32 v[6:7], s[10:11], v6, s18, v[2:3]
	global_load_dwordx4 v[10:13], v[4:5], off nt
	global_load_dwordx4 v[14:17], v[6:7], off nt
	v_or_b32_e32 v4, 48, v34
	v_mad_i64_i32 v[36:37], s[10:11], v4, s18, v[2:3]
	v_or_b32_e32 v4, 56, v34
	v_mad_i64_i32 v[70:71], s[10:11], v4, s18, v[2:3]
	global_load_dwordx4 v[6:9], v[36:37], off nt
	global_load_dwordx4 v[2:5], v[70:71], off nt
	s_and_b64 vcc, exec, s[0:1]
	s_cbranch_vccnz .LBB0_56
	v_ashrrev_i32_e32 v35, 31, v34
	v_lshl_add_u64 v[34:35], v[34:35], 2, s[4:5]
	global_load_dword v34, v[34:35], off
	v_or_b32_e32 v36, s8, v49
	v_ashrrev_i32_e32 v37, 31, v36
	v_lshl_add_u64 v[36:37], v[36:37], 2, s[4:5]
	s_waitcnt vmcnt(0) lgkmcnt(0)
	v_pk_mul_f32 v[70:71], v[28:29], v[34:35] op_sel_hi:[1,0]
	v_pk_mul_f32 v[34:35], v[26:27], v[34:35] op_sel_hi:[1,0]
	ds_write2_b32 v56, v34, v35 offset1:1
	ds_write2_b32 v56, v70, v71 offset0:2 offset1:3
	global_load_dword v34, v[36:37], off
	s_waitcnt vmcnt(0) lgkmcnt(0)
	v_pk_mul_f32 v[36:37], v[32:33], v[34:35] op_sel_hi:[1,0]
	v_pk_mul_f32 v[34:35], v[30:31], v[34:35] op_sel_hi:[1,0]
	s_cbranch_execnz .LBB0_48

.LBB0_64:
	s_ashr_i32 s8, s18, 31
	s_lshr_b32 s8, s8, 28
	s_add_i32 s8, s18, s8
	s_ashr_i32 s9, s8, 4
	s_lshl_b32 s8, s9, 6
	s_lshl_b32 s19, s9, 9
	s_sub_i32 s10, s17, s19
	v_or_b32_e32 v34, s8, v38
	s_ashr_i32 s11, s10, 31
	v_ashrrev_i32_e32 v35, 31, v34
	v_or_b32_e32 v6, 8, v34
	v_lshl_add_u64 v[2:3], s[10:11], 2, v[40:41]
	v_lshlrev_b64 v[4:5], 11, v[34:35]
	v_ashrrev_i32_e32 v7, 31, v6
	v_lshl_add_u64 v[4:5], v[2:3], 0, v[4:5]
	v_lshlrev_b64 v[6:7], 11, v[6:7]
	v_lshl_add_u64 v[6:7], v[2:3], 0, v[6:7]
	global_load_dwordx4 v[26:29], v[4:5], off nt
	global_load_dwordx4 v[30:33], v[6:7], off nt
	v_or_b32_e32 v4, 16, v34
	v_ashrrev_i32_e32 v5, 31, v4
	v_or_b32_e32 v6, 24, v34
	v_lshlrev_b64 v[4:5], 11, v[4:5]
	v_ashrrev_i32_e32 v7, 31, v6
	v_lshl_add_u64 v[4:5], v[2:3], 0, v[4:5]
	v_lshlrev_b64 v[6:7], 11, v[6:7]
	v_lshl_add_u64 v[6:7], v[2:3], 0, v[6:7]
	global_load_dwordx4 v[18:21], v[4:5], off nt
	global_load_dwordx4 v[22:25], v[6:7], off nt
	v_or_b32_e32 v4, 32, v34
	v_ashrrev_i32_e32 v5, 31, v4
	v_or_b32_e32 v6, 40, v34
	v_lshlrev_b64 v[4:5], 11, v[4:5]
	v_ashrrev_i32_e32 v7, 31, v6
	v_lshl_add_u64 v[4:5], v[2:3], 0, v[4:5]
	v_lshlrev_b64 v[6:7], 11, v[6:7]
	v_lshl_add_u64 v[6:7], v[2:3], 0, v[6:7]
	global_load_dwordx4 v[10:13], v[4:5], off nt
	global_load_dwordx4 v[14:17], v[6:7], off nt
	v_or_b32_e32 v4, 48, v34
	v_ashrrev_i32_e32 v5, 31, v4
	v_lshlrev_b64 v[4:5], 11, v[4:5]
	v_lshl_add_u64 v[36:37], v[2:3], 0, v[4:5]
	v_or_b32_e32 v4, 56, v34
	v_ashrrev_i32_e32 v5, 31, v4
	v_lshlrev_b64 v[4:5], 11, v[4:5]
	v_lshl_add_u64 v[60:61], v[2:3], 0, v[4:5]
	global_load_dwordx4 v[6:9], v[36:37], off nt
	global_load_dwordx4 v[2:5], v[60:61], off nt
	s_and_b64 vcc, exec, s[0:1]
	s_cbranch_vccnz .LBB0_75
	v_lshl_add_u64 v[34:35], v[34:35], 2, s[4:5]
	global_load_dword v34, v[34:35], off
	v_or_b32_e32 v36, s8, v49
	v_ashrrev_i32_e32 v37, 31, v36
	v_lshl_add_u64 v[36:37], v[36:37], 2, s[4:5]
	s_waitcnt vmcnt(0) lgkmcnt(0)
	v_pk_mul_f32 v[60:61], v[28:29], v[34:35] op_sel_hi:[1,0]
	v_pk_mul_f32 v[34:35], v[26:27], v[34:35] op_sel_hi:[1,0]
	ds_write2_b32 v56, v34, v35 offset1:1
	ds_write2_b32 v56, v60, v61 offset0:2 offset1:3
	global_load_dword v34, v[36:37], off
	s_waitcnt vmcnt(0) lgkmcnt(0)
	v_pk_mul_f32 v[36:37], v[32:33], v[34:35] op_sel_hi:[1,0]
	v_pk_mul_f32 v[34:35], v[30:31], v[34:35] op_sel_hi:[1,0]
	s_cbranch_execnz .LBB0_67

.LBB0_106:
	v_ashrrev_i32_e32 v7, 31, v6
	v_lshl_add_u64 v[18:19], v[6:7], 4, s[0:1]
	global_load_dwordx4 v[10:13], v[18:19], off nt
	global_load_dwordx4 v[14:17], v[18:19], off offset:16 nt
	v_add_u32_e32 v8, s4, v8
	v_cmp_lt_i32_e32 vcc, s10, v8
	v_add_u32_e32 v6, s5, v6
	s_or_b64 s[8:9], vcc, s[8:9]
	s_waitcnt vmcnt(0) lgkmcnt(0)
	v_cvt_pk_bf16_f32 v10, v10, v11
	v_cvt_pk_bf16_f32 v11, v12, v13
	v_cvt_pk_bf16_f32 v12, v14, v15
	v_cvt_pk_bf16_f32 v13, v16, v17
	global_store_dwordx4 v[4:5], v[10:13], off
	v_lshl_add_u64 v[4:5], v[4:5], 0, s[2:3]
	s_andn2_b64 exec, exec, s[8:9]
	s_cbranch_execnz .LBB0_106

.LBB0_1578:
	s_mul_hi_i32 s2, s13, 0x10624dd3
	s_lshr_b32 s3, s2, 31
	s_ashr_i32 s2, s2, 3
	s_add_i32 s2, s2, s3
	s_lshl_b32 s6, s2, 6
	s_mulk_i32 s2, 0xf060
	s_add_i32 s2, s10, s2
	s_ashr_i32 s3, s2, 31
	v_or_b32_e32 v27, s6, v24
	v_lshl_add_u64 v[0:1], s[2:3], 2, v[20:21]
	v_mad_i64_i32 v[2:3], s[14:15], v27, s29, v[0:1]
	global_load_dwordx4 v[28:31], v[2:3], off nt
	v_or_b32_e32 v2, 8, v27
	v_mad_i64_i32 v[2:3], s[14:15], v2, s29, v[0:1]
	global_load_dwordx4 v[36:39], v[2:3], off nt
	v_or_b32_e32 v2, 16, v27
	v_mad_i64_i32 v[2:3], s[14:15], v2, s29, v[0:1]
	global_load_dwordx4 v[40:43], v[2:3], off nt
	v_or_b32_e32 v2, 24, v27
	v_mad_i64_i32 v[2:3], s[14:15], v2, s29, v[0:1]
	global_load_dwordx4 v[16:19], v[2:3], off nt
	v_or_b32_e32 v2, 32, v27
	v_mad_i64_i32 v[2:3], s[14:15], v2, s29, v[0:1]
	global_load_dwordx4 v[12:15], v[2:3], off nt
	v_or_b32_e32 v2, 40, v27
	v_mad_i64_i32 v[2:3], s[14:15], v2, s29, v[0:1]
	global_load_dwordx4 v[8:11], v[2:3], off nt
	v_or_b32_e32 v2, 48, v27
	v_mad_i64_i32 v[2:3], s[14:15], v2, s29, v[0:1]
	global_load_dwordx4 v[4:7], v[2:3], off nt
	v_or_b32_e32 v2, 56, v27
	v_mad_i64_i32 v[0:1], s[14:15], v2, s29, v[0:1]
	global_load_dwordx4 v[0:3], v[0:1], off nt
	v_add_u32_e32 v27, 0x420, v26
	s_ashr_i32 s7, s6, 31
	s_add_i32 s13, s13, s16
	s_add_i32 s10, s10, s11
	s_cmpk_lt_i32 s13, 0x7d0
	s_waitcnt vmcnt(0) lgkmcnt(0)
	ds_write2_b32 v26, v28, v29 offset1:1
	ds_write2_b32 v26, v30, v31 offset0:2 offset1:3
	ds_write2_b32 v27, v36, v37 offset1:1
	v_add_u32_e32 v27, 0x428, v26
	ds_write2_b32 v27, v38, v39 offset1:1
	v_add_u32_e32 v27, 0x840, v26
	ds_write2_b32 v27, v40, v41 offset1:1
	v_add_u32_e32 v27, 0x848, v26
	ds_write2_b32 v27, v42, v43 offset1:1
	v_add_u32_e32 v27, 0xc60, v26
	ds_write2_b32 v27, v16, v17 offset1:1
	v_add_u32_e32 v16, 0xc68, v26
	ds_write2_b32 v16, v18, v19 offset1:1
	v_add_u32_e32 v16, 0x1080, v26
	ds_write2_b32 v16, v12, v13 offset1:1
	v_add_u32_e32 v12, 0x1088, v26
	ds_write2_b32 v12, v14, v15 offset1:1
	v_add_u32_e32 v12, 0x14a0, v26
	ds_write2_b32 v12, v8, v9 offset1:1
	v_add_u32_e32 v8, 0x14a8, v26
	ds_write2_b32 v8, v10, v11 offset1:1
	v_add_u32_e32 v8, 0x18c0, v26
	ds_write2_b32 v8, v4, v5 offset1:1
	v_add_u32_e32 v4, 0x18c8, v26
	ds_write2_b32 v4, v6, v7 offset1:1
	v_add_u32_e32 v4, 0x1ce0, v26
	ds_write2_b32 v4, v0, v1 offset1:1
	v_add_u32_e32 v0, 0x1ce8, v26
	ds_write2_b32 v0, v2, v3 offset1:1
	ds_read_b32 v0, v25
	ds_read_b32 v1, v25 offset:132
	v_lshl_add_u64 v[4:5], s[6:7], 1, v[22:23]
	s_waitcnt lgkmcnt(0)
	v_cvt_pk_bf16_f32 v0, v0, v1
	ds_read_b32 v1, v25 offset:264
	ds_read_b32 v2, v25 offset:396
	s_waitcnt lgkmcnt(0)
	v_cvt_pk_bf16_f32 v1, v1, v2
	ds_read_b32 v2, v25 offset:528
	ds_read_b32 v3, v25 offset:660
	s_waitcnt lgkmcnt(0)
	v_cvt_pk_bf16_f32 v2, v2, v3
	ds_read_b32 v3, v25 offset:792
	ds_read_b32 v6, v25 offset:924
	s_waitcnt lgkmcnt(0)
	v_cvt_pk_bf16_f32 v3, v3, v6
	v_add_u32_e32 v6, s2, v24
	v_ashrrev_i32_e32 v7, 31, v6
	v_lshlrev_b64 v[8:9], 11, v[6:7]
	v_lshl_add_u64 v[8:9], v[4:5], 0, v[8:9]
	global_store_dwordx4 v[8:9], v[0:3], off
	ds_read_b32 v0, v25 offset:32
	ds_read_b32 v1, v25 offset:164
	v_add_u32_e32 v8, 8, v6
	v_ashrrev_i32_e32 v9, 31, v8
	v_lshlrev_b64 v[8:9], 11, v[8:9]
	v_lshl_add_u64 v[8:9], v[4:5], 0, v[8:9]
	s_waitcnt lgkmcnt(0)
	v_cvt_pk_bf16_f32 v0, v0, v1
	ds_read_b32 v1, v25 offset:296
	ds_read_b32 v2, v25 offset:428
	s_waitcnt lgkmcnt(0)
	v_cvt_pk_bf16_f32 v1, v1, v2
	ds_read_b32 v2, v25 offset:560
	ds_read_b32 v3, v25 offset:692
	s_waitcnt lgkmcnt(0)
	v_cvt_pk_bf16_f32 v2, v2, v3
	ds_read_b32 v3, v25 offset:824
	ds_read_b32 v7, v25 offset:956
	s_waitcnt lgkmcnt(0)
	v_cvt_pk_bf16_f32 v3, v3, v7
	global_store_dwordx4 v[8:9], v[0:3], off
	ds_read_b32 v0, v25 offset:64
	ds_read_b32 v1, v25 offset:196
	v_add_u32_e32 v8, 16, v6
	v_ashrrev_i32_e32 v9, 31, v8
	v_lshlrev_b64 v[8:9], 11, v[8:9]
	v_lshl_add_u64 v[8:9], v[4:5], 0, v[8:9]
	s_waitcnt lgkmcnt(0)
	v_cvt_pk_bf16_f32 v0, v0, v1
	ds_read_b32 v1, v25 offset:328
	ds_read_b32 v2, v25 offset:460
	v_add_u32_e32 v6, 24, v6
	s_waitcnt lgkmcnt(0)
	v_cvt_pk_bf16_f32 v1, v1, v2
	ds_read_b32 v2, v25 offset:592
	ds_read_b32 v3, v25 offset:724
	s_waitcnt lgkmcnt(0)
	v_cvt_pk_bf16_f32 v2, v2, v3
	ds_read_b32 v3, v25 offset:856
	ds_read_b32 v7, v25 offset:988
	s_waitcnt lgkmcnt(0)
	v_cvt_pk_bf16_f32 v3, v3, v7
	global_store_dwordx4 v[8:9], v[0:3], off
	ds_read_b32 v0, v25 offset:96
	ds_read_b32 v1, v25 offset:228
	s_waitcnt lgkmcnt(0)
	v_cvt_pk_bf16_f32 v0, v0, v1
	ds_read_b32 v1, v25 offset:360
	ds_read_b32 v2, v25 offset:492
	s_waitcnt lgkmcnt(0)
	v_cvt_pk_bf16_f32 v1, v1, v2
	ds_read_b32 v2, v25 offset:624
	ds_read_b32 v3, v25 offset:756
	s_waitcnt lgkmcnt(0)
	v_cvt_pk_bf16_f32 v2, v2, v3
	ds_read_b32 v3, v25 offset:888
	ds_read_b32 v7, v25 offset:1020
	s_waitcnt lgkmcnt(0)
	v_cvt_pk_bf16_f32 v3, v3, v7
	v_ashrrev_i32_e32 v7, 31, v6
	v_lshlrev_b64 v[6:7], 11, v[6:7]
	v_lshl_add_u64 v[4:5], v[4:5], 0, v[6:7]
	global_store_dwordx4 v[4:5], v[0:3], off
	s_cbranch_scc1 .LBB0_1578

.LBB0_1581:
	s_ashr_i32 s4, s15, 31
	s_lshr_b32 s4, s4, 25
	s_add_i32 s4, s15, s4
	s_ashr_i32 s4, s4, 7
	s_lshl_b32 s10, s4, 6
	s_lshl_b32 s4, s4, 12
	s_sub_i32 s4, s13, s4
	s_ashr_i32 s5, s4, 31
	v_or_b32_e32 v27, s10, v24
	v_lshl_add_u64 v[0:1], s[4:5], 2, v[20:21]
	v_mad_i64_i32 v[2:3], s[18:19], v27, s29, v[0:1]
	global_load_dwordx4 v[28:31], v[2:3], off nt
	v_or_b32_e32 v2, 8, v27
	v_mad_i64_i32 v[2:3], s[18:19], v2, s29, v[0:1]
	global_load_dwordx4 v[36:39], v[2:3], off nt
	v_or_b32_e32 v2, 16, v27
	v_mad_i64_i32 v[2:3], s[18:19], v2, s29, v[0:1]
	global_load_dwordx4 v[40:43], v[2:3], off nt
	v_or_b32_e32 v2, 24, v27
	v_mad_i64_i32 v[2:3], s[18:19], v2, s29, v[0:1]
	global_load_dwordx4 v[16:19], v[2:3], off nt
	v_or_b32_e32 v2, 32, v27
	v_mad_i64_i32 v[2:3], s[18:19], v2, s29, v[0:1]
	global_load_dwordx4 v[12:15], v[2:3], off nt
	v_or_b32_e32 v2, 40, v27
	v_mad_i64_i32 v[2:3], s[18:19], v2, s29, v[0:1]
	global_load_dwordx4 v[8:11], v[2:3], off nt
	v_or_b32_e32 v2, 48, v27
	v_mad_i64_i32 v[2:3], s[18:19], v2, s29, v[0:1]
	global_load_dwordx4 v[4:7], v[2:3], off nt
	v_or_b32_e32 v2, 56, v27
	v_mad_i64_i32 v[0:1], s[18:19], v2, s29, v[0:1]
	global_load_dwordx4 v[0:3], v[0:1], off nt
	v_add_u32_e32 v27, 0x420, v26
	s_ashr_i32 s11, s10, 31
	s_add_i32 s15, s15, s16
	s_add_i32 s13, s13, s14
	s_cmpk_lt_i32 s15, 0x800
	s_waitcnt vmcnt(0) lgkmcnt(0)
	ds_write2_b32 v26, v28, v29 offset1:1
	ds_write2_b32 v26, v30, v31 offset0:2 offset1:3
	ds_write2_b32 v27, v36, v37 offset1:1
	v_add_u32_e32 v27, 0x428, v26
	ds_write2_b32 v27, v38, v39 offset1:1
	v_add_u32_e32 v27, 0x840, v26
	ds_write2_b32 v27, v40, v41 offset1:1
	v_add_u32_e32 v27, 0x848, v26
	ds_write2_b32 v27, v42, v43 offset1:1
	v_add_u32_e32 v27, 0xc60, v26
	ds_write2_b32 v27, v16, v17 offset1:1
	v_add_u32_e32 v16, 0xc68, v26
	ds_write2_b32 v16, v18, v19 offset1:1
	v_add_u32_e32 v16, 0x1080, v26
	ds_write2_b32 v16, v12, v13 offset1:1
	v_add_u32_e32 v12, 0x1088, v26
	ds_write2_b32 v12, v14, v15 offset1:1
	v_add_u32_e32 v12, 0x14a0, v26
	ds_write2_b32 v12, v8, v9 offset1:1
	v_add_u32_e32 v8, 0x14a8, v26
	ds_write2_b32 v8, v10, v11 offset1:1
	v_add_u32_e32 v8, 0x18c0, v26
	ds_write2_b32 v8, v4, v5 offset1:1
	v_add_u32_e32 v4, 0x18c8, v26
	ds_write2_b32 v4, v6, v7 offset1:1
	v_add_u32_e32 v4, 0x1ce0, v26
	ds_write2_b32 v4, v0, v1 offset1:1
	v_add_u32_e32 v0, 0x1ce8, v26
	ds_write2_b32 v0, v2, v3 offset1:1
	ds_read_b32 v0, v25
	ds_read_b32 v1, v25 offset:132
	v_lshl_add_u64 v[4:5], s[10:11], 1, v[22:23]
	s_waitcnt lgkmcnt(0)
	v_cvt_pk_bf16_f32 v0, v0, v1
	ds_read_b32 v1, v25 offset:264
	ds_read_b32 v2, v25 offset:396
	s_waitcnt lgkmcnt(0)
	v_cvt_pk_bf16_f32 v1, v1, v2
	ds_read_b32 v2, v25 offset:528
	ds_read_b32 v3, v25 offset:660
	s_waitcnt lgkmcnt(0)
	v_cvt_pk_bf16_f32 v2, v2, v3
	ds_read_b32 v3, v25 offset:792
	ds_read_b32 v6, v25 offset:924
	s_waitcnt lgkmcnt(0)
	v_cvt_pk_bf16_f32 v3, v3, v6
	v_add_u32_e32 v6, s4, v24
	v_ashrrev_i32_e32 v7, 31, v6
	v_lshlrev_b64 v[8:9], 11, v[6:7]
	v_lshl_add_u64 v[8:9], v[4:5], 0, v[8:9]
	global_store_dwordx4 v[8:9], v[0:3], off
	ds_read_b32 v0, v25 offset:32
	ds_read_b32 v1, v25 offset:164
	v_add_u32_e32 v8, 8, v6
	v_ashrrev_i32_e32 v9, 31, v8
	v_lshlrev_b64 v[8:9], 11, v[8:9]
	v_lshl_add_u64 v[8:9], v[4:5], 0, v[8:9]
	s_waitcnt lgkmcnt(0)
	v_cvt_pk_bf16_f32 v0, v0, v1
	ds_read_b32 v1, v25 offset:296
	ds_read_b32 v2, v25 offset:428
	s_waitcnt lgkmcnt(0)
	v_cvt_pk_bf16_f32 v1, v1, v2
	ds_read_b32 v2, v25 offset:560
	ds_read_b32 v3, v25 offset:692
	s_waitcnt lgkmcnt(0)
	v_cvt_pk_bf16_f32 v2, v2, v3
	ds_read_b32 v3, v25 offset:824
	ds_read_b32 v7, v25 offset:956
	s_waitcnt lgkmcnt(0)
	v_cvt_pk_bf16_f32 v3, v3, v7
	global_store_dwordx4 v[8:9], v[0:3], off
	ds_read_b32 v0, v25 offset:64
	ds_read_b32 v1, v25 offset:196
	v_add_u32_e32 v8, 16, v6
	v_ashrrev_i32_e32 v9, 31, v8
	v_lshlrev_b64 v[8:9], 11, v[8:9]
	v_lshl_add_u64 v[8:9], v[4:5], 0, v[8:9]
	s_waitcnt lgkmcnt(0)
	v_cvt_pk_bf16_f32 v0, v0, v1
	ds_read_b32 v1, v25 offset:328
	ds_read_b32 v2, v25 offset:460
	v_add_u32_e32 v6, 24, v6
	s_waitcnt lgkmcnt(0)
	v_cvt_pk_bf16_f32 v1, v1, v2
	ds_read_b32 v2, v25 offset:592
	ds_read_b32 v3, v25 offset:724
	s_waitcnt lgkmcnt(0)
	v_cvt_pk_bf16_f32 v2, v2, v3
	ds_read_b32 v3, v25 offset:856
	ds_read_b32 v7, v25 offset:988
	s_waitcnt lgkmcnt(0)
	v_cvt_pk_bf16_f32 v3, v3, v7
	global_store_dwordx4 v[8:9], v[0:3], off
	ds_read_b32 v0, v25 offset:96
	ds_read_b32 v1, v25 offset:228
	s_waitcnt lgkmcnt(0)
	v_cvt_pk_bf16_f32 v0, v0, v1
	ds_read_b32 v1, v25 offset:360
	ds_read_b32 v2, v25 offset:492
	s_waitcnt lgkmcnt(0)
	v_cvt_pk_bf16_f32 v1, v1, v2
	ds_read_b32 v2, v25 offset:624
	ds_read_b32 v3, v25 offset:756
	s_waitcnt lgkmcnt(0)
	v_cvt_pk_bf16_f32 v2, v2, v3
	ds_read_b32 v3, v25 offset:888
	ds_read_b32 v7, v25 offset:1020
	s_waitcnt lgkmcnt(0)
	v_cvt_pk_bf16_f32 v3, v3, v7
	v_ashrrev_i32_e32 v7, 31, v6
	v_lshlrev_b64 v[6:7], 11, v[6:7]
	v_lshl_add_u64 v[4:5], v[4:5], 0, v[6:7]
	global_store_dwordx4 v[4:5], v[0:3], off
	s_cbranch_scc1 .LBB0_1581

.LBB0_1584:
	s_ashr_i32 s4, s13, 31
	s_lshr_b32 s4, s4, 25
	s_add_i32 s4, s13, s4
	s_ashr_i32 s4, s4, 7
	s_lshl_b32 s6, s4, 6
	s_lshl_b32 s4, s4, 12
	s_sub_i32 s4, s10, s4
	v_or_b32_e32 v0, s6, v33
	s_ashr_i32 s5, s4, 31
	v_ashrrev_i32_e32 v1, 31, v0
	v_lshl_add_u64 v[2:3], s[4:5], 2, v[28:29]
	v_lshlrev_b64 v[4:5], 14, v[0:1]
	v_lshl_add_u64 v[4:5], v[2:3], 0, v[4:5]
	global_load_dwordx4 v[38:41], v[4:5], off nt
	v_or_b32_e32 v4, 8, v0
	v_ashrrev_i32_e32 v5, 31, v4
	v_lshlrev_b64 v[4:5], 14, v[4:5]
	v_lshl_add_u64 v[4:5], v[2:3], 0, v[4:5]
	global_load_dwordx4 v[24:27], v[4:5], off nt
	v_or_b32_e32 v4, 16, v0
	v_ashrrev_i32_e32 v5, 31, v4
	v_lshlrev_b64 v[4:5], 14, v[4:5]
	v_lshl_add_u64 v[4:5], v[2:3], 0, v[4:5]
	global_load_dwordx4 v[20:23], v[4:5], off nt
	v_or_b32_e32 v4, 24, v0
	v_ashrrev_i32_e32 v5, 31, v4
	v_lshlrev_b64 v[4:5], 14, v[4:5]
	v_lshl_add_u64 v[4:5], v[2:3], 0, v[4:5]
	global_load_dwordx4 v[16:19], v[4:5], off nt
	v_or_b32_e32 v4, 32, v0
	v_ashrrev_i32_e32 v5, 31, v4
	v_lshlrev_b64 v[4:5], 14, v[4:5]
	v_lshl_add_u64 v[4:5], v[2:3], 0, v[4:5]
	global_load_dwordx4 v[12:15], v[4:5], off nt
	v_or_b32_e32 v4, 40, v0
	v_ashrrev_i32_e32 v5, 31, v4
	v_lshlrev_b64 v[4:5], 14, v[4:5]
	v_lshl_add_u64 v[4:5], v[2:3], 0, v[4:5]
	global_load_dwordx4 v[8:11], v[4:5], off nt
	v_or_b32_e32 v4, 48, v0
	v_ashrrev_i32_e32 v5, 31, v4
	v_lshlrev_b64 v[4:5], 14, v[4:5]
	v_or_b32_e32 v0, 56, v0
	v_lshl_add_u64 v[4:5], v[2:3], 0, v[4:5]
	v_ashrrev_i32_e32 v1, 31, v0
	global_load_dwordx4 v[4:7], v[4:5], off nt
	v_lshlrev_b64 v[0:1], 14, v[0:1]
	v_lshl_add_u64 v[0:1], v[2:3], 0, v[0:1]
	global_load_dwordx4 v[0:3], v[0:1], off nt
	s_ashr_i32 s7, s6, 31
	s_add_i32 s13, s13, s16
	s_add_i32 s10, s10, s11
	s_cmpk_lt_i32 s13, 0x800
	s_waitcnt vmcnt(0) lgkmcnt(0)
	ds_write2_b32 v37, v38, v39 offset1:1
	ds_write2_b32 v37, v40, v41 offset0:2 offset1:3
	v_add_u32_e32 v38, 0x420, v37
	ds_write2_b32 v38, v24, v25 offset1:1
	v_add_u32_e32 v24, 0x428, v37
	ds_write2_b32 v24, v26, v27 offset1:1
	v_add_u32_e32 v24, 0x840, v37
	ds_write2_b32 v24, v20, v21 offset1:1
	v_add_u32_e32 v20, 0x848, v37
	ds_write2_b32 v20, v22, v23 offset1:1
	v_add_u32_e32 v20, 0xc60, v37
	ds_write2_b32 v20, v16, v17 offset1:1
	v_add_u32_e32 v16, 0xc68, v37
	ds_write2_b32 v16, v18, v19 offset1:1
	v_add_u32_e32 v16, 0x1080, v37
	ds_write2_b32 v16, v12, v13 offset1:1
	v_add_u32_e32 v12, 0x1088, v37
	ds_write2_b32 v12, v14, v15 offset1:1
	v_add_u32_e32 v12, 0x14a0, v37
	ds_write2_b32 v12, v8, v9 offset1:1
	v_add_u32_e32 v8, 0x14a8, v37
	ds_write2_b32 v8, v10, v11 offset1:1
	v_add_u32_e32 v8, 0x18c0, v37
	ds_write2_b32 v8, v4, v5 offset1:1
	v_add_u32_e32 v4, 0x18c8, v37
	ds_write2_b32 v4, v6, v7 offset1:1
	v_add_u32_e32 v4, 0x1ce0, v37
	ds_write2_b32 v4, v0, v1 offset1:1
	v_add_u32_e32 v0, 0x1ce8, v37
	ds_write2_b32 v0, v2, v3 offset1:1
	ds_read_b32 v0, v36
	ds_read_b32 v1, v36 offset:132
	v_lshl_add_u64 v[4:5], s[6:7], 1, v[30:31]
	s_waitcnt lgkmcnt(0)
	v_cvt_pk_bf16_f32 v0, v0, v1
	ds_read_b32 v1, v36 offset:264
	ds_read_b32 v2, v36 offset:396
	s_waitcnt lgkmcnt(0)
	v_cvt_pk_bf16_f32 v1, v1, v2
	ds_read_b32 v2, v36 offset:528
	ds_read_b32 v3, v36 offset:660
	s_waitcnt lgkmcnt(0)
	v_cvt_pk_bf16_f32 v2, v2, v3
	ds_read_b32 v3, v36 offset:792
	ds_read_b32 v6, v36 offset:924
	s_waitcnt lgkmcnt(0)
	v_cvt_pk_bf16_f32 v3, v3, v6
	v_add_u32_e32 v6, s4, v33
	v_ashrrev_i32_e32 v7, 31, v6
	v_lshlrev_b64 v[8:9], 11, v[6:7]
	v_lshl_add_u64 v[8:9], v[4:5], 0, v[8:9]
	global_store_dwordx4 v[8:9], v[0:3], off
	ds_read_b32 v0, v36 offset:32
	ds_read_b32 v1, v36 offset:164
	v_add_u32_e32 v8, 8, v6
	v_ashrrev_i32_e32 v9, 31, v8
	v_lshlrev_b64 v[8:9], 11, v[8:9]
	v_lshl_add_u64 v[8:9], v[4:5], 0, v[8:9]
	s_waitcnt lgkmcnt(0)
	v_cvt_pk_bf16_f32 v0, v0, v1
	ds_read_b32 v1, v36 offset:296
	ds_read_b32 v2, v36 offset:428
	s_waitcnt lgkmcnt(0)
	v_cvt_pk_bf16_f32 v1, v1, v2
	ds_read_b32 v2, v36 offset:560
	ds_read_b32 v3, v36 offset:692
	s_waitcnt lgkmcnt(0)
	v_cvt_pk_bf16_f32 v2, v2, v3
	ds_read_b32 v3, v36 offset:824
	ds_read_b32 v7, v36 offset:956
	s_waitcnt lgkmcnt(0)
	v_cvt_pk_bf16_f32 v3, v3, v7
	global_store_dwordx4 v[8:9], v[0:3], off
	ds_read_b32 v0, v36 offset:64
	ds_read_b32 v1, v36 offset:196
	v_add_u32_e32 v8, 16, v6
	v_ashrrev_i32_e32 v9, 31, v8
	v_lshlrev_b64 v[8:9], 11, v[8:9]
	v_lshl_add_u64 v[8:9], v[4:5], 0, v[8:9]
	s_waitcnt lgkmcnt(0)
	v_cvt_pk_bf16_f32 v0, v0, v1
	ds_read_b32 v1, v36 offset:328
	ds_read_b32 v2, v36 offset:460
	v_add_u32_e32 v6, 24, v6
	s_waitcnt lgkmcnt(0)
	v_cvt_pk_bf16_f32 v1, v1, v2
	ds_read_b32 v2, v36 offset:592
	ds_read_b32 v3, v36 offset:724
	s_waitcnt lgkmcnt(0)
	v_cvt_pk_bf16_f32 v2, v2, v3
	ds_read_b32 v3, v36 offset:856
	ds_read_b32 v7, v36 offset:988
	s_waitcnt lgkmcnt(0)
	v_cvt_pk_bf16_f32 v3, v3, v7
	global_store_dwordx4 v[8:9], v[0:3], off
	ds_read_b32 v0, v36 offset:96
	ds_read_b32 v1, v36 offset:228
	s_waitcnt lgkmcnt(0)
	v_cvt_pk_bf16_f32 v0, v0, v1
	ds_read_b32 v1, v36 offset:360
	ds_read_b32 v2, v36 offset:492
	s_waitcnt lgkmcnt(0)
	v_cvt_pk_bf16_f32 v1, v1, v2
	ds_read_b32 v2, v36 offset:624
	ds_read_b32 v3, v36 offset:756
	s_waitcnt lgkmcnt(0)
	v_cvt_pk_bf16_f32 v2, v2, v3
	ds_read_b32 v3, v36 offset:888
	ds_read_b32 v7, v36 offset:1020
	s_waitcnt lgkmcnt(0)
	v_cvt_pk_bf16_f32 v3, v3, v7
	v_ashrrev_i32_e32 v7, 31, v6
	v_lshlrev_b64 v[6:7], 11, v[6:7]
	v_lshl_add_u64 v[4:5], v[4:5], 0, v[6:7]
	global_store_dwordx4 v[4:5], v[0:3], off
	s_cbranch_scc1 .LBB0_1584

.LBB0_1589:
	s_ashr_i32 s2, s10, 31
	s_lshr_b32 s2, s2, 27
	s_add_i32 s2, s10, s2
	s_ashr_i32 s2, s2, 5
	s_lshl_b32 s4, s2, 6
	s_lshl_b32 s2, s2, 10
	s_sub_i32 s2, s6, s2
	v_or_b32_e32 v0, s4, v35
	s_ashr_i32 s3, s2, 31
	v_ashrrev_i32_e32 v1, 31, v0
	v_lshl_add_u64 v[2:3], s[2:3], 2, v[30:31]
	v_lshlrev_b64 v[4:5], 12, v[0:1]
	v_lshl_add_u64 v[4:5], v[2:3], 0, v[4:5]
	global_load_dwordx4 v[42:45], v[4:5], off nt
	v_or_b32_e32 v4, 8, v0
	v_ashrrev_i32_e32 v5, 31, v4
	v_lshlrev_b64 v[4:5], 12, v[4:5]
	v_lshl_add_u64 v[4:5], v[2:3], 0, v[4:5]
	global_load_dwordx4 v[24:27], v[4:5], off nt
	v_or_b32_e32 v4, 16, v0
	v_ashrrev_i32_e32 v5, 31, v4
	v_lshlrev_b64 v[4:5], 12, v[4:5]
	v_lshl_add_u64 v[4:5], v[2:3], 0, v[4:5]
	global_load_dwordx4 v[20:23], v[4:5], off nt
	v_or_b32_e32 v4, 24, v0
	v_ashrrev_i32_e32 v5, 31, v4
	v_lshlrev_b64 v[4:5], 12, v[4:5]
	v_lshl_add_u64 v[4:5], v[2:3], 0, v[4:5]
	global_load_dwordx4 v[16:19], v[4:5], off nt
	v_or_b32_e32 v4, 32, v0
	v_ashrrev_i32_e32 v5, 31, v4
	v_lshlrev_b64 v[4:5], 12, v[4:5]
	v_lshl_add_u64 v[4:5], v[2:3], 0, v[4:5]
	global_load_dwordx4 v[12:15], v[4:5], off nt
	v_or_b32_e32 v4, 40, v0
	v_ashrrev_i32_e32 v5, 31, v4
	v_lshlrev_b64 v[4:5], 12, v[4:5]
	v_lshl_add_u64 v[4:5], v[2:3], 0, v[4:5]
	global_load_dwordx4 v[8:11], v[4:5], off nt
	v_or_b32_e32 v4, 48, v0
	v_ashrrev_i32_e32 v5, 31, v4
	v_lshlrev_b64 v[4:5], 12, v[4:5]
	v_or_b32_e32 v0, 56, v0
	v_lshl_add_u64 v[4:5], v[2:3], 0, v[4:5]
	v_ashrrev_i32_e32 v1, 31, v0
	global_load_dwordx4 v[4:7], v[4:5], off nt
	v_lshlrev_b64 v[0:1], 12, v[0:1]
	v_lshl_add_u64 v[0:1], v[2:3], 0, v[0:1]
	global_load_dwordx4 v[0:3], v[0:1], off nt
	v_add_u32_e32 v41, 0x420, v40
	s_ashr_i32 s5, s4, 31
	s_add_i32 s10, s10, s16
	s_add_i32 s6, s6, s7
	s_cmpk_lt_i32 s10, 0x800
	s_waitcnt vmcnt(0) lgkmcnt(0)
	ds_write2_b32 v40, v42, v43 offset1:1
	ds_write2_b32 v40, v44, v45 offset0:2 offset1:3
	ds_write2_b32 v41, v24, v25 offset1:1
	v_add_u32_e32 v24, 0x428, v40
	ds_write2_b32 v24, v26, v27 offset1:1
	v_add_u32_e32 v24, 0x840, v40
	ds_write2_b32 v24, v20, v21 offset1:1
	v_add_u32_e32 v20, 0x848, v40
	ds_write2_b32 v20, v22, v23 offset1:1
	v_add_u32_e32 v20, 0xc60, v40
	ds_write2_b32 v20, v16, v17 offset1:1
	v_add_u32_e32 v16, 0xc68, v40
	ds_write2_b32 v16, v18, v19 offset1:1
	v_add_u32_e32 v16, 0x1080, v40
	ds_write2_b32 v16, v12, v13 offset1:1
	v_add_u32_e32 v12, 0x1088, v40
	ds_write2_b32 v12, v14, v15 offset1:1
	v_add_u32_e32 v12, 0x14a0, v40
	ds_write2_b32 v12, v8, v9 offset1:1
	v_add_u32_e32 v8, 0x14a8, v40
	ds_write2_b32 v8, v10, v11 offset1:1
	v_add_u32_e32 v8, 0x18c0, v40
	ds_write2_b32 v8, v4, v5 offset1:1
	v_add_u32_e32 v4, 0x18c8, v40
	ds_write2_b32 v4, v6, v7 offset1:1
	v_add_u32_e32 v4, 0x1ce0, v40
	ds_write2_b32 v4, v0, v1 offset1:1
	v_add_u32_e32 v0, 0x1ce8, v40
	ds_write2_b32 v0, v2, v3 offset1:1
	ds_read_b32 v0, v29
	ds_read_b32 v1, v29 offset:132
	v_lshl_add_u64 v[4:5], s[4:5], 1, v[32:33]
	s_waitcnt lgkmcnt(0)
	v_cvt_pk_bf16_f32 v0, v0, v1
	ds_read_b32 v1, v29 offset:264
	ds_read_b32 v2, v29 offset:396
	s_waitcnt lgkmcnt(0)
	v_cvt_pk_bf16_f32 v1, v1, v2
	ds_read_b32 v2, v29 offset:528
	ds_read_b32 v3, v29 offset:660
	s_waitcnt lgkmcnt(0)
	v_cvt_pk_bf16_f32 v2, v2, v3
	ds_read_b32 v3, v29 offset:792
	ds_read_b32 v6, v29 offset:924
	s_waitcnt lgkmcnt(0)
	v_cvt_pk_bf16_f32 v3, v3, v6
	v_add_u32_e32 v6, s2, v35
	v_ashrrev_i32_e32 v7, 31, v6
	v_lshlrev_b64 v[8:9], 13, v[6:7]
	v_lshl_add_u64 v[8:9], v[4:5], 0, v[8:9]
	global_store_dwordx4 v[8:9], v[0:3], off
	ds_read_b32 v0, v29 offset:32
	ds_read_b32 v1, v29 offset:164
	v_add_u32_e32 v8, 8, v6
	v_ashrrev_i32_e32 v9, 31, v8
	v_lshlrev_b64 v[8:9], 13, v[8:9]
	v_lshl_add_u64 v[8:9], v[4:5], 0, v[8:9]
	s_waitcnt lgkmcnt(0)
	v_cvt_pk_bf16_f32 v0, v0, v1
	ds_read_b32 v1, v29 offset:296
	ds_read_b32 v2, v29 offset:428
	s_waitcnt lgkmcnt(0)
	v_cvt_pk_bf16_f32 v1, v1, v2
	ds_read_b32 v2, v29 offset:560
	ds_read_b32 v3, v29 offset:692
	s_waitcnt lgkmcnt(0)
	v_cvt_pk_bf16_f32 v2, v2, v3
	ds_read_b32 v3, v29 offset:824
	ds_read_b32 v7, v29 offset:956
	s_waitcnt lgkmcnt(0)
	v_cvt_pk_bf16_f32 v3, v3, v7
	global_store_dwordx4 v[8:9], v[0:3], off
	ds_read_b32 v0, v29 offset:64
	ds_read_b32 v1, v29 offset:196
	v_add_u32_e32 v8, 16, v6
	v_ashrrev_i32_e32 v9, 31, v8
	v_lshlrev_b64 v[8:9], 13, v[8:9]
	v_lshl_add_u64 v[8:9], v[4:5], 0, v[8:9]
	s_waitcnt lgkmcnt(0)
	v_cvt_pk_bf16_f32 v0, v0, v1
	ds_read_b32 v1, v29 offset:328
	ds_read_b32 v2, v29 offset:460
	v_add_u32_e32 v6, 24, v6
	s_waitcnt lgkmcnt(0)
	v_cvt_pk_bf16_f32 v1, v1, v2
	ds_read_b32 v2, v29 offset:592
	ds_read_b32 v3, v29 offset:724
	s_waitcnt lgkmcnt(0)
	v_cvt_pk_bf16_f32 v2, v2, v3
	ds_read_b32 v3, v29 offset:856
	ds_read_b32 v7, v29 offset:988
	s_waitcnt lgkmcnt(0)
	v_cvt_pk_bf16_f32 v3, v3, v7
	global_store_dwordx4 v[8:9], v[0:3], off
	ds_read_b32 v0, v29 offset:96
	ds_read_b32 v1, v29 offset:228
	s_waitcnt lgkmcnt(0)
	v_cvt_pk_bf16_f32 v0, v0, v1
	ds_read_b32 v1, v29 offset:360
	ds_read_b32 v2, v29 offset:492
	s_waitcnt lgkmcnt(0)
	v_cvt_pk_bf16_f32 v1, v1, v2
	ds_read_b32 v2, v29 offset:624
	ds_read_b32 v3, v29 offset:756
	s_waitcnt lgkmcnt(0)
	v_cvt_pk_bf16_f32 v2, v2, v3
	ds_read_b32 v3, v29 offset:888
	ds_read_b32 v7, v29 offset:1020
	s_waitcnt lgkmcnt(0)
	v_cvt_pk_bf16_f32 v3, v3, v7
	v_ashrrev_i32_e32 v7, 31, v6
	v_lshlrev_b64 v[6:7], 13, v[6:7]
	v_lshl_add_u64 v[4:5], v[4:5], 0, v[6:7]
	global_store_dwordx4 v[4:5], v[0:3], off
	s_cbranch_scc1 .LBB0_1589
	v_mov_b32_e32 v40, v35
	v_mov_b32_e32 v0, v28
	v_mov_b32_e32 v2, v34

.LBB0_1595:
	s_ashr_i32 s6, s14, 31
	s_lshr_b32 s6, s6, 27
	s_add_i32 s6, s14, s6
	s_ashr_i32 s6, s6, 5
	s_lshl_b32 s10, s6, 6
	s_lshl_b32 s6, s6, 10
	s_sub_i32 s6, s12, s6
	v_or_b32_e32 v34, s10, v40
	s_ashr_i32 s7, s6, 31
	v_ashrrev_i32_e32 v35, 31, v34
	v_or_b32_e32 v4, 8, v34
	v_lshl_add_u64 v[20:21], s[6:7], 2, v[16:17]
	v_lshlrev_b64 v[0:1], 12, v[34:35]
	v_ashrrev_i32_e32 v5, 31, v4
	v_or_b32_e32 v8, 16, v34
	v_lshl_add_u64 v[0:1], v[20:21], 0, v[0:1]
	v_lshlrev_b64 v[4:5], 12, v[4:5]
	v_ashrrev_i32_e32 v9, 31, v8
	v_or_b32_e32 v22, 24, v34
	global_load_dwordx4 v[0:3], v[0:1], off nt
	v_lshl_add_u64 v[4:5], v[20:21], 0, v[4:5]
	v_lshlrev_b64 v[8:9], 12, v[8:9]
	v_ashrrev_i32_e32 v23, 31, v22
	v_or_b32_e32 v26, 32, v34
	global_load_dwordx4 v[4:7], v[4:5], off nt
	v_lshl_add_u64 v[8:9], v[20:21], 0, v[8:9]
	v_lshlrev_b64 v[22:23], 12, v[22:23]
	v_ashrrev_i32_e32 v27, 31, v26
	global_load_dwordx4 v[8:11], v[8:9], off nt
	v_lshl_add_u64 v[22:23], v[20:21], 0, v[22:23]
	v_lshlrev_b64 v[26:27], 12, v[26:27]
	v_or_b32_e32 v30, 40, v34
	global_load_dwordx4 v[22:25], v[22:23], off nt
	v_lshl_add_u64 v[26:27], v[20:21], 0, v[26:27]
	v_ashrrev_i32_e32 v31, 31, v30
	global_load_dwordx4 v[26:29], v[26:27], off nt
	v_lshlrev_b64 v[30:31], 12, v[30:31]
	v_or_b32_e32 v42, 48, v34
	v_lshl_add_u64 v[30:31], v[20:21], 0, v[30:31]
	v_ashrrev_i32_e32 v43, 31, v42
	global_load_dwordx4 v[30:33], v[30:31], off nt
	v_lshlrev_b64 v[42:43], 12, v[42:43]
	v_or_b32_e32 v34, 56, v34
	v_lshl_add_u64 v[42:43], v[20:21], 0, v[42:43]
	v_ashrrev_i32_e32 v35, 31, v34
	global_load_dwordx4 v[42:45], v[42:43], off nt
	v_lshlrev_b64 v[34:35], 12, v[34:35]
	v_lshl_add_u64 v[20:21], v[20:21], 0, v[34:35]
	global_load_dwordx4 v[58:61], v[20:21], off nt
	v_add_u32_e32 v20, v53, v46
	s_ashr_i32 s11, s10, 31
	s_add_i32 s14, s14, s16
	s_add_i32 s12, s12, s13
	s_cmpk_lt_i32 s14, 0x80
	s_waitcnt vmcnt(0) lgkmcnt(0)
	ds_write2_b32 v20, v0, v1 offset1:1
	ds_write2_b32 v20, v2, v3 offset0:2 offset1:3
	v_add_u32_e32 v0, v53, v48
	ds_write2_b32 v0, v4, v5 offset1:1
	ds_write2_b32 v0, v6, v7 offset0:2 offset1:3
	v_add_u32_e32 v0, v53, v50
	ds_write2_b32 v0, v8, v9 offset1:1
	ds_write2_b32 v0, v10, v11 offset0:2 offset1:3
	v_add_u32_e32 v0, v53, v52
	ds_write2_b32 v0, v22, v23 offset1:1
	ds_write2_b32 v0, v24, v25 offset0:2 offset1:3
	v_add_u32_e32 v0, 0x1080, v20
	v_lshl_add_u64 v[4:5], s[10:11], 1, v[18:19]
	ds_write2_b32 v0, v26, v27 offset1:1
	v_add_u32_e32 v0, 0x1088, v20
	ds_write2_b32 v0, v28, v29 offset1:1
	v_add_u32_e32 v0, 0x14a0, v20
	ds_write2_b32 v0, v30, v31 offset1:1
	v_add_u32_e32 v0, 0x14a8, v20
	ds_write2_b32 v0, v32, v33 offset1:1
	v_add_u32_e32 v0, 0x18c0, v20
	ds_write2_b32 v0, v42, v43 offset1:1
	v_add_u32_e32 v0, 0x18c8, v20
	ds_write2_b32 v0, v44, v45 offset1:1
	v_add_u32_e32 v0, 0x1ce0, v20
	ds_write2_b32 v0, v58, v59 offset1:1
	v_add_u32_e32 v0, 0x1ce8, v20
	ds_write2_b32 v0, v60, v61 offset1:1
	ds_read2_b32 v[0:1], v54 offset1:33
	ds_read2_b32 v[2:3], v54 offset0:66 offset1:99
	ds_read2_b32 v[6:7], v54 offset0:198 offset1:231
	s_waitcnt lgkmcnt(2)
	v_cvt_pk_bf16_f32 v0, v0, v1
	s_waitcnt lgkmcnt(1)
	v_cvt_pk_bf16_f32 v1, v2, v3
	ds_read2_b32 v[2:3], v54 offset0:132 offset1:165
	s_waitcnt lgkmcnt(0)
	v_cvt_pk_bf16_f32 v2, v2, v3
	v_cvt_pk_bf16_f32 v3, v6, v7
	v_add_u32_e32 v6, s6, v40
	v_ashrrev_i32_e32 v7, 31, v6
	v_lshlrev_b64 v[6:7], 9, v[6:7]
	v_lshl_add_u64 v[6:7], v[4:5], 0, v[6:7]
	global_store_dwordx4 v[6:7], v[0:3], off
	ds_read2_b32 v[0:1], v55 offset1:33
	ds_read2_b32 v[2:3], v55 offset0:66 offset1:99
	ds_read2_b32 v[6:7], v55 offset0:198 offset1:231
	s_waitcnt lgkmcnt(0)
	v_cvt_pk_bf16_f32 v0, v0, v1
	v_cvt_pk_bf16_f32 v1, v2, v3
	ds_read2_b32 v[2:3], v55 offset0:132 offset1:165
	s_waitcnt lgkmcnt(0)
	v_cvt_pk_bf16_f32 v2, v2, v3
	v_cvt_pk_bf16_f32 v3, v6, v7
	v_add_u32_e32 v6, s6, v47
	v_ashrrev_i32_e32 v7, 31, v6
	v_lshlrev_b64 v[6:7], 9, v[6:7]
	v_lshl_add_u64 v[6:7], v[4:5], 0, v[6:7]
	global_store_dwordx4 v[6:7], v[0:3], off
	ds_read2_b32 v[0:1], v56 offset1:33
	ds_read2_b32 v[2:3], v56 offset0:66 offset1:99
	ds_read2_b32 v[6:7], v56 offset0:198 offset1:231
	s_waitcnt lgkmcnt(0)
	v_cvt_pk_bf16_f32 v0, v0, v1
	v_cvt_pk_bf16_f32 v1, v2, v3
	ds_read2_b32 v[2:3], v56 offset0:132 offset1:165
	s_waitcnt lgkmcnt(0)
	v_cvt_pk_bf16_f32 v2, v2, v3
	v_cvt_pk_bf16_f32 v3, v6, v7
	v_add_u32_e32 v6, s6, v49
	v_ashrrev_i32_e32 v7, 31, v6
	v_lshlrev_b64 v[6:7], 9, v[6:7]
	v_lshl_add_u64 v[6:7], v[4:5], 0, v[6:7]
	global_store_dwordx4 v[6:7], v[0:3], off
	ds_read2_b32 v[0:1], v57 offset1:33
	ds_read2_b32 v[2:3], v57 offset0:66 offset1:99
	ds_read2_b32 v[6:7], v57 offset0:198 offset1:231
	s_waitcnt lgkmcnt(0)
	v_cvt_pk_bf16_f32 v0, v0, v1
	v_cvt_pk_bf16_f32 v1, v2, v3
	ds_read2_b32 v[2:3], v57 offset0:132 offset1:165
	s_waitcnt lgkmcnt(0)
	v_cvt_pk_bf16_f32 v2, v2, v3
	v_cvt_pk_bf16_f32 v3, v6, v7
	v_add_u32_e32 v6, s6, v51
	v_ashrrev_i32_e32 v7, 31, v6
	v_lshlrev_b64 v[6:7], 9, v[6:7]
	v_lshl_add_u64 v[4:5], v[4:5], 0, v[6:7]
	global_store_dwordx4 v[4:5], v[0:3], off
	s_cbranch_scc1 .LBB0_1595
	s_branch .LBB0_1592

.LBB0_1598:
	s_ashr_i32 s6, s14, 31
	s_lshr_b32 s6, s6, 27
	s_add_i32 s6, s14, s6
	s_ashr_i32 s6, s6, 5
	s_lshl_b32 s10, s6, 6
	s_lshl_b32 s6, s6, 10
	s_sub_i32 s6, s12, s6
	v_or_b32_e32 v42, s10, v40
	s_ashr_i32 s7, s6, 31
	v_ashrrev_i32_e32 v43, 31, v42
	v_or_b32_e32 v4, 8, v42
	v_lshl_add_u64 v[18:19], s[6:7], 2, v[14:15]
	v_lshlrev_b64 v[0:1], 12, v[42:43]
	v_ashrrev_i32_e32 v5, 31, v4
	v_or_b32_e32 v8, 16, v42
	v_lshl_add_u64 v[0:1], v[18:19], 0, v[0:1]
	v_lshlrev_b64 v[4:5], 12, v[4:5]
	v_ashrrev_i32_e32 v9, 31, v8
	v_or_b32_e32 v20, 24, v42
	global_load_dwordx4 v[0:3], v[0:1], off nt
	v_lshl_add_u64 v[4:5], v[18:19], 0, v[4:5]
	v_lshlrev_b64 v[8:9], 12, v[8:9]
	v_ashrrev_i32_e32 v21, 31, v20
	v_or_b32_e32 v24, 32, v42
	global_load_dwordx4 v[4:7], v[4:5], off nt
	v_lshl_add_u64 v[8:9], v[18:19], 0, v[8:9]
	v_lshlrev_b64 v[20:21], 12, v[20:21]
	v_ashrrev_i32_e32 v25, 31, v24
	global_load_dwordx4 v[8:11], v[8:9], off nt
	v_lshl_add_u64 v[20:21], v[18:19], 0, v[20:21]
	v_lshlrev_b64 v[24:25], 12, v[24:25]
	v_or_b32_e32 v28, 40, v42
	global_load_dwordx4 v[20:23], v[20:21], off nt
	v_lshl_add_u64 v[24:25], v[18:19], 0, v[24:25]
	v_ashrrev_i32_e32 v29, 31, v28
	global_load_dwordx4 v[24:27], v[24:25], off nt
	v_lshlrev_b64 v[28:29], 12, v[28:29]
	v_or_b32_e32 v32, 48, v42
	v_lshl_add_u64 v[28:29], v[18:19], 0, v[28:29]
	v_ashrrev_i32_e32 v33, 31, v32
	global_load_dwordx4 v[28:31], v[28:29], off nt
	v_lshlrev_b64 v[32:33], 12, v[32:33]
	v_or_b32_e32 v42, 56, v42
	v_lshl_add_u64 v[32:33], v[18:19], 0, v[32:33]
	v_ashrrev_i32_e32 v43, 31, v42
	global_load_dwordx4 v[32:35], v[32:33], off nt
	v_lshlrev_b64 v[42:43], 12, v[42:43]
	v_lshl_add_u64 v[18:19], v[18:19], 0, v[42:43]
	global_load_dwordx4 v[42:45], v[18:19], off nt
	v_add_u32_e32 v18, v53, v46
	s_ashr_i32 s11, s10, 31
	s_add_i32 s14, s14, s16
	s_add_i32 s12, s12, s13
	s_cmpk_lt_i32 s14, 0x200
	s_waitcnt vmcnt(0) lgkmcnt(0)
	ds_write2_b32 v18, v0, v1 offset1:1
	ds_write2_b32 v18, v2, v3 offset0:2 offset1:3
	v_add_u32_e32 v0, v53, v48
	ds_write2_b32 v0, v4, v5 offset1:1
	ds_write2_b32 v0, v6, v7 offset0:2 offset1:3
	v_add_u32_e32 v0, v53, v50
	ds_write2_b32 v0, v8, v9 offset1:1
	ds_write2_b32 v0, v10, v11 offset0:2 offset1:3
	v_add_u32_e32 v0, v53, v52
	ds_write2_b32 v0, v20, v21 offset1:1
	ds_write2_b32 v0, v22, v23 offset0:2 offset1:3
	v_add_u32_e32 v0, 0x1080, v18
	v_lshl_add_u64 v[4:5], s[10:11], 1, v[16:17]
	ds_write2_b32 v0, v24, v25 offset1:1
	v_add_u32_e32 v0, 0x1088, v18
	ds_write2_b32 v0, v26, v27 offset1:1
	v_add_u32_e32 v0, 0x14a0, v18
	ds_write2_b32 v0, v28, v29 offset1:1
	v_add_u32_e32 v0, 0x14a8, v18
	ds_write2_b32 v0, v30, v31 offset1:1
	v_add_u32_e32 v0, 0x18c0, v18
	ds_write2_b32 v0, v32, v33 offset1:1
	v_add_u32_e32 v0, 0x18c8, v18
	ds_write2_b32 v0, v34, v35 offset1:1
	v_add_u32_e32 v0, 0x1ce0, v18
	ds_write2_b32 v0, v42, v43 offset1:1
	v_add_u32_e32 v0, 0x1ce8, v18
	ds_write2_b32 v0, v44, v45 offset1:1
	ds_read2_b32 v[0:1], v54 offset1:33
	ds_read2_b32 v[2:3], v54 offset0:66 offset1:99
	ds_read2_b32 v[6:7], v54 offset0:198 offset1:231
	s_waitcnt lgkmcnt(2)
	v_cvt_pk_bf16_f32 v0, v0, v1
	s_waitcnt lgkmcnt(1)
	v_cvt_pk_bf16_f32 v1, v2, v3
	ds_read2_b32 v[2:3], v54 offset0:132 offset1:165
	s_waitcnt lgkmcnt(0)
	v_cvt_pk_bf16_f32 v2, v2, v3
	v_cvt_pk_bf16_f32 v3, v6, v7
	v_add_u32_e32 v6, s6, v40
	v_ashrrev_i32_e32 v7, 31, v6
	v_lshlrev_b64 v[6:7], 11, v[6:7]
	v_lshl_add_u64 v[6:7], v[4:5], 0, v[6:7]
	global_store_dwordx4 v[6:7], v[0:3], off
	ds_read2_b32 v[0:1], v55 offset1:33
	ds_read2_b32 v[2:3], v55 offset0:66 offset1:99
	ds_read2_b32 v[6:7], v55 offset0:198 offset1:231
	s_waitcnt lgkmcnt(0)
	v_cvt_pk_bf16_f32 v0, v0, v1
	v_cvt_pk_bf16_f32 v1, v2, v3
	ds_read2_b32 v[2:3], v55 offset0:132 offset1:165
	s_waitcnt lgkmcnt(0)
	v_cvt_pk_bf16_f32 v2, v2, v3
	v_cvt_pk_bf16_f32 v3, v6, v7
	v_add_u32_e32 v6, s6, v47
	v_ashrrev_i32_e32 v7, 31, v6
	v_lshlrev_b64 v[6:7], 11, v[6:7]
	v_lshl_add_u64 v[6:7], v[4:5], 0, v[6:7]
	global_store_dwordx4 v[6:7], v[0:3], off
	ds_read2_b32 v[0:1], v56 offset1:33
	ds_read2_b32 v[2:3], v56 offset0:66 offset1:99
	ds_read2_b32 v[6:7], v56 offset0:198 offset1:231
	s_waitcnt lgkmcnt(0)
	v_cvt_pk_bf16_f32 v0, v0, v1
	v_cvt_pk_bf16_f32 v1, v2, v3
	ds_read2_b32 v[2:3], v56 offset0:132 offset1:165
	s_waitcnt lgkmcnt(0)
	v_cvt_pk_bf16_f32 v2, v2, v3
	v_cvt_pk_bf16_f32 v3, v6, v7
	v_add_u32_e32 v6, s6, v49
	v_ashrrev_i32_e32 v7, 31, v6
	v_lshlrev_b64 v[6:7], 11, v[6:7]
	v_lshl_add_u64 v[6:7], v[4:5], 0, v[6:7]
	global_store_dwordx4 v[6:7], v[0:3], off
	ds_read2_b32 v[0:1], v57 offset1:33
	ds_read2_b32 v[2:3], v57 offset0:66 offset1:99
	ds_read2_b32 v[6:7], v57 offset0:198 offset1:231
	s_waitcnt lgkmcnt(0)
	v_cvt_pk_bf16_f32 v0, v0, v1
	v_cvt_pk_bf16_f32 v1, v2, v3
	ds_read2_b32 v[2:3], v57 offset0:132 offset1:165
	s_waitcnt lgkmcnt(0)
	v_cvt_pk_bf16_f32 v2, v2, v3
	v_cvt_pk_bf16_f32 v3, v6, v7
	v_add_u32_e32 v6, s6, v51
	v_ashrrev_i32_e32 v7, 31, v6
	v_lshlrev_b64 v[6:7], 11, v[6:7]
	v_lshl_add_u64 v[4:5], v[4:5], 0, v[6:7]
	global_store_dwordx4 v[4:5], v[0:3], off
	s_cbranch_scc1 .LBB0_1598

.LBB0_1601:
	s_ashr_i32 s4, s12, 31
	s_lshr_b32 s4, s4, 27
	s_add_i32 s4, s12, s4
	s_ashr_i32 s4, s4, 5
	s_lshl_b32 s6, s4, 6
	s_lshl_b32 s4, s4, 10
	s_sub_i32 s4, s10, s4
	v_or_b32_e32 v42, s6, v40
	s_ashr_i32 s5, s4, 31
	v_ashrrev_i32_e32 v43, 31, v42
	v_or_b32_e32 v4, 8, v42
	v_lshl_add_u64 v[18:19], s[4:5], 2, v[14:15]
	v_lshlrev_b64 v[0:1], 12, v[42:43]
	v_ashrrev_i32_e32 v5, 31, v4
	v_or_b32_e32 v8, 16, v42
	v_lshl_add_u64 v[0:1], v[18:19], 0, v[0:1]
	v_lshlrev_b64 v[4:5], 12, v[4:5]
	v_ashrrev_i32_e32 v9, 31, v8
	v_or_b32_e32 v20, 24, v42
	global_load_dwordx4 v[0:3], v[0:1], off nt
	v_lshl_add_u64 v[4:5], v[18:19], 0, v[4:5]
	v_lshlrev_b64 v[8:9], 12, v[8:9]
	v_ashrrev_i32_e32 v21, 31, v20
	v_or_b32_e32 v24, 32, v42
	global_load_dwordx4 v[4:7], v[4:5], off nt
	v_lshl_add_u64 v[8:9], v[18:19], 0, v[8:9]
	v_lshlrev_b64 v[20:21], 12, v[20:21]
	v_ashrrev_i32_e32 v25, 31, v24
	global_load_dwordx4 v[8:11], v[8:9], off nt
	v_lshl_add_u64 v[20:21], v[18:19], 0, v[20:21]
	v_lshlrev_b64 v[24:25], 12, v[24:25]
	v_or_b32_e32 v28, 40, v42
	global_load_dwordx4 v[20:23], v[20:21], off nt
	v_lshl_add_u64 v[24:25], v[18:19], 0, v[24:25]
	v_ashrrev_i32_e32 v29, 31, v28
	global_load_dwordx4 v[24:27], v[24:25], off nt
	v_lshlrev_b64 v[28:29], 12, v[28:29]
	v_or_b32_e32 v32, 48, v42
	v_lshl_add_u64 v[28:29], v[18:19], 0, v[28:29]
	v_ashrrev_i32_e32 v33, 31, v32
	global_load_dwordx4 v[28:31], v[28:29], off nt
	v_lshlrev_b64 v[32:33], 12, v[32:33]
	v_or_b32_e32 v42, 56, v42
	v_lshl_add_u64 v[32:33], v[18:19], 0, v[32:33]
	v_ashrrev_i32_e32 v43, 31, v42
	global_load_dwordx4 v[32:35], v[32:33], off nt
	v_lshlrev_b64 v[42:43], 12, v[42:43]
	v_lshl_add_u64 v[18:19], v[18:19], 0, v[42:43]
	global_load_dwordx4 v[42:45], v[18:19], off nt
	v_add_u32_e32 v18, v53, v46
	s_ashr_i32 s7, s6, 31
	s_add_i32 s12, s12, s16
	s_add_i32 s10, s10, s11
	s_cmpk_lt_i32 s12, 0x200
	s_waitcnt vmcnt(0) lgkmcnt(0)
	ds_write2_b32 v18, v0, v1 offset1:1
	ds_write2_b32 v18, v2, v3 offset0:2 offset1:3
	v_add_u32_e32 v0, v53, v48
	ds_write2_b32 v0, v4, v5 offset1:1
	ds_write2_b32 v0, v6, v7 offset0:2 offset1:3
	v_add_u32_e32 v0, v53, v50
	ds_write2_b32 v0, v8, v9 offset1:1
	ds_write2_b32 v0, v10, v11 offset0:2 offset1:3
	v_add_u32_e32 v0, v53, v52
	ds_write2_b32 v0, v20, v21 offset1:1
	ds_write2_b32 v0, v22, v23 offset0:2 offset1:3
	v_add_u32_e32 v0, 0x1080, v18
	v_lshl_add_u64 v[4:5], s[6:7], 1, v[16:17]
	ds_write2_b32 v0, v24, v25 offset1:1
	v_add_u32_e32 v0, 0x1088, v18
	ds_write2_b32 v0, v26, v27 offset1:1
	v_add_u32_e32 v0, 0x14a0, v18
	ds_write2_b32 v0, v28, v29 offset1:1
	v_add_u32_e32 v0, 0x14a8, v18
	ds_write2_b32 v0, v30, v31 offset1:1
	v_add_u32_e32 v0, 0x18c0, v18
	ds_write2_b32 v0, v32, v33 offset1:1
	v_add_u32_e32 v0, 0x18c8, v18
	ds_write2_b32 v0, v34, v35 offset1:1
	v_add_u32_e32 v0, 0x1ce0, v18
	ds_write2_b32 v0, v42, v43 offset1:1
	v_add_u32_e32 v0, 0x1ce8, v18
	ds_write2_b32 v0, v44, v45 offset1:1
	ds_read2_b32 v[0:1], v54 offset1:33
	ds_read2_b32 v[2:3], v54 offset0:66 offset1:99
	ds_read2_b32 v[6:7], v54 offset0:198 offset1:231
	s_waitcnt lgkmcnt(2)
	v_cvt_pk_bf16_f32 v0, v0, v1
	s_waitcnt lgkmcnt(1)
	v_cvt_pk_bf16_f32 v1, v2, v3
	ds_read2_b32 v[2:3], v54 offset0:132 offset1:165
	s_waitcnt lgkmcnt(0)
	v_cvt_pk_bf16_f32 v2, v2, v3
	v_cvt_pk_bf16_f32 v3, v6, v7
	v_add_u32_e32 v6, s4, v40
	v_ashrrev_i32_e32 v7, 31, v6
	v_lshlrev_b64 v[6:7], 11, v[6:7]
	v_lshl_add_u64 v[6:7], v[4:5], 0, v[6:7]
	global_store_dwordx4 v[6:7], v[0:3], off
	ds_read2_b32 v[0:1], v55 offset1:33
	ds_read2_b32 v[2:3], v55 offset0:66 offset1:99
	ds_read2_b32 v[6:7], v55 offset0:198 offset1:231
	s_waitcnt lgkmcnt(0)
	v_cvt_pk_bf16_f32 v0, v0, v1
	v_cvt_pk_bf16_f32 v1, v2, v3
	ds_read2_b32 v[2:3], v55 offset0:132 offset1:165
	s_waitcnt lgkmcnt(0)
	v_cvt_pk_bf16_f32 v2, v2, v3
	v_cvt_pk_bf16_f32 v3, v6, v7
	v_add_u32_e32 v6, s4, v47
	v_ashrrev_i32_e32 v7, 31, v6
	v_lshlrev_b64 v[6:7], 11, v[6:7]
	v_lshl_add_u64 v[6:7], v[4:5], 0, v[6:7]
	global_store_dwordx4 v[6:7], v[0:3], off
	ds_read2_b32 v[0:1], v56 offset1:33
	ds_read2_b32 v[2:3], v56 offset0:66 offset1:99
	ds_read2_b32 v[6:7], v56 offset0:198 offset1:231
	s_waitcnt lgkmcnt(0)
	v_cvt_pk_bf16_f32 v0, v0, v1
	v_cvt_pk_bf16_f32 v1, v2, v3
	ds_read2_b32 v[2:3], v56 offset0:132 offset1:165
	s_waitcnt lgkmcnt(0)
	v_cvt_pk_bf16_f32 v2, v2, v3
	v_cvt_pk_bf16_f32 v3, v6, v7
	v_add_u32_e32 v6, s4, v49
	v_ashrrev_i32_e32 v7, 31, v6
	v_lshlrev_b64 v[6:7], 11, v[6:7]
	v_lshl_add_u64 v[6:7], v[4:5], 0, v[6:7]
	global_store_dwordx4 v[6:7], v[0:3], off
	ds_read2_b32 v[0:1], v57 offset1:33
	ds_read2_b32 v[2:3], v57 offset0:66 offset1:99
	ds_read2_b32 v[6:7], v57 offset0:198 offset1:231
	s_waitcnt lgkmcnt(0)
	v_cvt_pk_bf16_f32 v0, v0, v1
	v_cvt_pk_bf16_f32 v1, v2, v3
	ds_read2_b32 v[2:3], v57 offset0:132 offset1:165
	s_waitcnt lgkmcnt(0)
	v_cvt_pk_bf16_f32 v2, v2, v3
	v_cvt_pk_bf16_f32 v3, v6, v7
	v_add_u32_e32 v6, s4, v51
	v_ashrrev_i32_e32 v7, 31, v6
	v_lshlrev_b64 v[6:7], 11, v[6:7]
	v_lshl_add_u64 v[4:5], v[4:5], 0, v[6:7]
	global_store_dwordx4 v[4:5], v[0:3], off
	s_cbranch_scc1 .LBB0_1601

.LBB0_1604:
	s_ashr_i32 s2, s10, 31
	s_lshr_b32 s2, s2, 27
	s_add_i32 s2, s10, s2
	s_ashr_i32 s2, s2, 5
	s_lshl_b32 s4, s2, 6
	s_lshl_b32 s2, s2, 10
	s_sub_i32 s2, s6, s2
	v_or_b32_e32 v42, s4, v40
	s_ashr_i32 s3, s2, 31
	v_ashrrev_i32_e32 v43, 31, v42
	v_or_b32_e32 v4, 8, v42
	v_lshl_add_u64 v[18:19], s[2:3], 2, v[14:15]
	v_lshlrev_b64 v[0:1], 12, v[42:43]
	v_ashrrev_i32_e32 v5, 31, v4
	v_or_b32_e32 v8, 16, v42
	v_lshl_add_u64 v[0:1], v[18:19], 0, v[0:1]
	v_lshlrev_b64 v[4:5], 12, v[4:5]
	v_ashrrev_i32_e32 v9, 31, v8
	v_or_b32_e32 v20, 24, v42
	global_load_dwordx4 v[0:3], v[0:1], off nt
	v_lshl_add_u64 v[4:5], v[18:19], 0, v[4:5]
	v_lshlrev_b64 v[8:9], 12, v[8:9]
	v_ashrrev_i32_e32 v21, 31, v20
	v_or_b32_e32 v24, 32, v42
	global_load_dwordx4 v[4:7], v[4:5], off nt
	v_lshl_add_u64 v[8:9], v[18:19], 0, v[8:9]
	v_lshlrev_b64 v[20:21], 12, v[20:21]
	v_ashrrev_i32_e32 v25, 31, v24
	global_load_dwordx4 v[8:11], v[8:9], off nt
	v_lshl_add_u64 v[20:21], v[18:19], 0, v[20:21]
	v_lshlrev_b64 v[24:25], 12, v[24:25]
	v_or_b32_e32 v28, 40, v42
	global_load_dwordx4 v[20:23], v[20:21], off nt
	v_lshl_add_u64 v[24:25], v[18:19], 0, v[24:25]
	v_ashrrev_i32_e32 v29, 31, v28
	global_load_dwordx4 v[24:27], v[24:25], off nt
	v_lshlrev_b64 v[28:29], 12, v[28:29]
	v_or_b32_e32 v32, 48, v42
	v_lshl_add_u64 v[28:29], v[18:19], 0, v[28:29]
	v_ashrrev_i32_e32 v33, 31, v32
	global_load_dwordx4 v[28:31], v[28:29], off nt
	v_lshlrev_b64 v[32:33], 12, v[32:33]
	v_or_b32_e32 v42, 56, v42
	v_lshl_add_u64 v[32:33], v[18:19], 0, v[32:33]
	v_ashrrev_i32_e32 v43, 31, v42
	global_load_dwordx4 v[32:35], v[32:33], off nt
	v_lshlrev_b64 v[42:43], 12, v[42:43]
	v_lshl_add_u64 v[18:19], v[18:19], 0, v[42:43]
	global_load_dwordx4 v[42:45], v[18:19], off nt
	v_add_u32_e32 v18, v53, v46
	s_ashr_i32 s5, s4, 31
	s_add_i32 s10, s10, s16
	s_add_i32 s6, s6, s7
	s_cmpk_lt_i32 s10, 0x80
	s_waitcnt vmcnt(0) lgkmcnt(0)
	ds_write2_b32 v18, v0, v1 offset1:1
	ds_write2_b32 v18, v2, v3 offset0:2 offset1:3
	v_add_u32_e32 v0, v53, v48
	ds_write2_b32 v0, v4, v5 offset1:1
	ds_write2_b32 v0, v6, v7 offset0:2 offset1:3
	v_add_u32_e32 v0, v53, v50
	ds_write2_b32 v0, v8, v9 offset1:1
	ds_write2_b32 v0, v10, v11 offset0:2 offset1:3
	v_add_u32_e32 v0, v53, v52
	ds_write2_b32 v0, v20, v21 offset1:1
	ds_write2_b32 v0, v22, v23 offset0:2 offset1:3
	v_add_u32_e32 v0, 0x1080, v18
	v_lshl_add_u64 v[4:5], s[4:5], 1, v[16:17]
	ds_write2_b32 v0, v24, v25 offset1:1
	v_add_u32_e32 v0, 0x1088, v18
	ds_write2_b32 v0, v26, v27 offset1:1
	v_add_u32_e32 v0, 0x14a0, v18
	ds_write2_b32 v0, v28, v29 offset1:1
	v_add_u32_e32 v0, 0x14a8, v18
	ds_write2_b32 v0, v30, v31 offset1:1
	v_add_u32_e32 v0, 0x18c0, v18
	ds_write2_b32 v0, v32, v33 offset1:1
	v_add_u32_e32 v0, 0x18c8, v18
	ds_write2_b32 v0, v34, v35 offset1:1
	v_add_u32_e32 v0, 0x1ce0, v18
	ds_write2_b32 v0, v42, v43 offset1:1
	v_add_u32_e32 v0, 0x1ce8, v18
	ds_write2_b32 v0, v44, v45 offset1:1
	ds_read2_b32 v[0:1], v54 offset1:33
	ds_read2_b32 v[2:3], v54 offset0:66 offset1:99
	ds_read2_b32 v[6:7], v54 offset0:198 offset1:231
	s_waitcnt lgkmcnt(2)
	v_cvt_pk_bf16_f32 v0, v0, v1
	s_waitcnt lgkmcnt(1)
	v_cvt_pk_bf16_f32 v1, v2, v3
	ds_read2_b32 v[2:3], v54 offset0:132 offset1:165
	s_waitcnt lgkmcnt(0)
	v_cvt_pk_bf16_f32 v2, v2, v3
	v_cvt_pk_bf16_f32 v3, v6, v7
	v_add_u32_e32 v6, s2, v40
	v_ashrrev_i32_e32 v7, 31, v6
	v_lshlrev_b64 v[6:7], 9, v[6:7]
	v_lshl_add_u64 v[6:7], v[4:5], 0, v[6:7]
	global_store_dwordx4 v[6:7], v[0:3], off
	ds_read2_b32 v[0:1], v55 offset1:33
	ds_read2_b32 v[2:3], v55 offset0:66 offset1:99
	ds_read2_b32 v[6:7], v55 offset0:198 offset1:231
	s_waitcnt lgkmcnt(0)
	v_cvt_pk_bf16_f32 v0, v0, v1
	v_cvt_pk_bf16_f32 v1, v2, v3
	ds_read2_b32 v[2:3], v55 offset0:132 offset1:165
	s_waitcnt lgkmcnt(0)
	v_cvt_pk_bf16_f32 v2, v2, v3
	v_cvt_pk_bf16_f32 v3, v6, v7
	v_add_u32_e32 v6, s2, v47
	v_ashrrev_i32_e32 v7, 31, v6
	v_lshlrev_b64 v[6:7], 9, v[6:7]
	v_lshl_add_u64 v[6:7], v[4:5], 0, v[6:7]
	global_store_dwordx4 v[6:7], v[0:3], off
	ds_read2_b32 v[0:1], v56 offset1:33
	ds_read2_b32 v[2:3], v56 offset0:66 offset1:99
	ds_read2_b32 v[6:7], v56 offset0:198 offset1:231
	s_waitcnt lgkmcnt(0)
	v_cvt_pk_bf16_f32 v0, v0, v1
	v_cvt_pk_bf16_f32 v1, v2, v3
	ds_read2_b32 v[2:3], v56 offset0:132 offset1:165
	s_waitcnt lgkmcnt(0)
	v_cvt_pk_bf16_f32 v2, v2, v3
	v_cvt_pk_bf16_f32 v3, v6, v7
	v_add_u32_e32 v6, s2, v49
	v_ashrrev_i32_e32 v7, 31, v6
	v_lshlrev_b64 v[6:7], 9, v[6:7]
	v_lshl_add_u64 v[6:7], v[4:5], 0, v[6:7]
	global_store_dwordx4 v[6:7], v[0:3], off
	ds_read2_b32 v[0:1], v57 offset1:33
	ds_read2_b32 v[2:3], v57 offset0:66 offset1:99
	ds_read2_b32 v[6:7], v57 offset0:198 offset1:231
	s_waitcnt lgkmcnt(0)
	v_cvt_pk_bf16_f32 v0, v0, v1
	v_cvt_pk_bf16_f32 v1, v2, v3
	ds_read2_b32 v[2:3], v57 offset0:132 offset1:165
	s_waitcnt lgkmcnt(0)
	v_cvt_pk_bf16_f32 v2, v2, v3
	v_cvt_pk_bf16_f32 v3, v6, v7
	v_add_u32_e32 v6, s2, v51
	v_ashrrev_i32_e32 v7, 31, v6
	v_lshlrev_b64 v[6:7], 9, v[6:7]
	v_lshl_add_u64 v[4:5], v[4:5], 0, v[6:7]
	global_store_dwordx4 v[4:5], v[0:3], off
	s_cbranch_scc1 .LBB0_1604

.LBB0_1608:
	s_mul_hi_i32 s2, s19, 0x2aaaaaab
	s_lshr_b32 s3, s2, 31
	s_ashr_i32 s2, s2, 1
	s_add_i32 s2, s2, s3
	s_lshl_b32 s12, s2, 6
	s_mulk_i32 s2, 0xfe80
	s_add_i32 s10, s17, s2
	v_or_b32_e32 v32, s12, v40
	s_ashr_i32 s11, s10, 31
	v_lshl_add_u64 v[0:1], s[10:11], 2, v[42:43]
	v_or_b32_e32 v4, 8, v32
	v_mad_i64_i32 v[2:3], s[2:3], v32, s31, v[0:1]
	v_mad_i64_i32 v[4:5], s[2:3], v4, s31, v[0:1]
	global_load_dwordx4 v[24:27], v[2:3], off nt
	global_load_dwordx4 v[28:31], v[4:5], off nt
	v_or_b32_e32 v2, 16, v32
	v_or_b32_e32 v4, 24, v32
	v_mad_i64_i32 v[2:3], s[2:3], v2, s31, v[0:1]
	v_mad_i64_i32 v[4:5], s[2:3], v4, s31, v[0:1]
	global_load_dwordx4 v[16:19], v[2:3], off nt
	global_load_dwordx4 v[20:23], v[4:5], off nt
	v_or_b32_e32 v2, 32, v32
	v_or_b32_e32 v4, 40, v32
	v_mad_i64_i32 v[2:3], s[2:3], v2, s31, v[0:1]
	v_mad_i64_i32 v[4:5], s[2:3], v4, s31, v[0:1]
	global_load_dwordx4 v[8:11], v[2:3], off nt
	global_load_dwordx4 v[12:15], v[4:5], off nt
	v_or_b32_e32 v2, 48, v32
	v_or_b32_e32 v4, 56, v32
	v_mad_i64_i32 v[2:3], s[2:3], v2, s31, v[0:1]
	v_mad_i64_i32 v[0:1], s[2:3], v4, s31, v[0:1]
	global_load_dwordx4 v[4:7], v[2:3], off nt
	s_nop 0
	global_load_dwordx4 v[0:3], v[0:1], off nt
	v_cndmask_b32_e64 v33, 0, 1, s[6:7]
	v_cmp_ne_u32_e64 s[2:3], 1, v33
	s_andn2_b64 vcc, exec, s[6:7]
	s_cbranch_vccnz .LBB0_1619
	v_ashrrev_i32_e32 v33, 31, v32
	v_lshl_add_u64 v[32:33], v[32:33], 2, s[4:5]
	global_load_dword v32, v[32:33], off offset:1024
	v_add_u32_e32 v66, v53, v46
	s_waitcnt vmcnt(0) lgkmcnt(0)
	v_pk_mul_f32 v[34:35], v[26:27], v[32:33] op_sel_hi:[1,0]
	v_pk_mul_f32 v[32:33], v[24:25], v[32:33] op_sel_hi:[1,0]
	ds_write2_b32 v66, v32, v33 offset1:1
	ds_write2_b32 v66, v34, v35 offset0:2 offset1:3
	v_or_b32_e32 v32, s12, v47
	v_ashrrev_i32_e32 v33, 31, v32
	v_lshl_add_u64 v[32:33], v[32:33], 2, s[4:5]
	global_load_dword v32, v[32:33], off offset:1024
	s_waitcnt vmcnt(0) lgkmcnt(0)
	v_pk_mul_f32 v[34:35], v[30:31], v[32:33] op_sel_hi:[1,0]
	v_pk_mul_f32 v[32:33], v[28:29], v[32:33] op_sel_hi:[1,0]
	s_cbranch_execnz .LBB0_1611

.LBB0_1627:
	s_ashr_i32 s2, s26, 31
	s_lshr_b32 s2, s2, 28
	s_add_i32 s2, s26, s2
	s_ashr_i32 s2, s2, 4
	s_lshl_b32 s12, s2, 6
	s_lshl_b32 s19, s2, 9
	v_or_b32_e32 v32, s12, v40
	s_sub_i32 s2, s17, s19
	v_or_b32_e32 v4, 8, v32
	s_ashr_i32 s3, s2, 31
	v_ashrrev_i32_e32 v33, 31, v32
	v_ashrrev_i32_e32 v5, 31, v4
	v_lshl_add_u64 v[0:1], s[2:3], 2, v[38:39]
	v_lshlrev_b64 v[2:3], 11, v[32:33]
	v_lshlrev_b64 v[4:5], 11, v[4:5]
	v_lshl_add_u64 v[2:3], v[0:1], 0, v[2:3]
	v_lshl_add_u64 v[4:5], v[0:1], 0, v[4:5]
	global_load_dwordx4 v[24:27], v[2:3], off nt
	global_load_dwordx4 v[28:31], v[4:5], off nt
	v_or_b32_e32 v2, 16, v32
	v_or_b32_e32 v4, 24, v32
	v_ashrrev_i32_e32 v3, 31, v2
	v_ashrrev_i32_e32 v5, 31, v4
	v_lshlrev_b64 v[2:3], 11, v[2:3]
	v_lshlrev_b64 v[4:5], 11, v[4:5]
	v_lshl_add_u64 v[2:3], v[0:1], 0, v[2:3]
	v_lshl_add_u64 v[4:5], v[0:1], 0, v[4:5]
	global_load_dwordx4 v[16:19], v[2:3], off nt
	global_load_dwordx4 v[20:23], v[4:5], off nt
	v_or_b32_e32 v2, 32, v32
	v_or_b32_e32 v4, 40, v32
	v_ashrrev_i32_e32 v3, 31, v2
	v_ashrrev_i32_e32 v5, 31, v4
	v_lshlrev_b64 v[2:3], 11, v[2:3]
	v_lshlrev_b64 v[4:5], 11, v[4:5]
	v_lshl_add_u64 v[2:3], v[0:1], 0, v[2:3]
	v_lshl_add_u64 v[4:5], v[0:1], 0, v[4:5]
	global_load_dwordx4 v[8:11], v[2:3], off nt
	global_load_dwordx4 v[12:15], v[4:5], off nt
	v_or_b32_e32 v2, 48, v32
	v_or_b32_e32 v4, 56, v32
	v_ashrrev_i32_e32 v3, 31, v2
	v_ashrrev_i32_e32 v5, 31, v4
	v_lshlrev_b64 v[2:3], 11, v[2:3]
	v_lshlrev_b64 v[4:5], 11, v[4:5]
	v_lshl_add_u64 v[2:3], v[0:1], 0, v[2:3]
	v_lshl_add_u64 v[0:1], v[0:1], 0, v[4:5]
	global_load_dwordx4 v[4:7], v[2:3], off nt
	s_nop 0
	global_load_dwordx4 v[0:3], v[0:1], off nt
	v_cndmask_b32_e64 v34, 0, 1, s[10:11]
	v_cmp_ne_u32_e64 s[2:3], 1, v34
	s_andn2_b64 vcc, exec, s[10:11]
	v_add_u32_e32 v58, v53, v46
	s_cbranch_vccnz .LBB0_1638
	v_lshl_add_u64 v[32:33], v[32:33], 2, s[6:7]
	global_load_dword v32, v[32:33], off offset:512
	s_waitcnt vmcnt(0) lgkmcnt(0)
	v_pk_mul_f32 v[34:35], v[26:27], v[32:33] op_sel_hi:[1,0]
	v_pk_mul_f32 v[32:33], v[24:25], v[32:33] op_sel_hi:[1,0]
	ds_write2_b32 v58, v32, v33 offset1:1
	ds_write2_b32 v58, v34, v35 offset0:2 offset1:3
	v_or_b32_e32 v32, s12, v47
	v_ashrrev_i32_e32 v33, 31, v32
	v_lshl_add_u64 v[32:33], v[32:33], 2, s[6:7]
	global_load_dword v32, v[32:33], off offset:512
	s_waitcnt vmcnt(0) lgkmcnt(0)
	v_pk_mul_f32 v[34:35], v[30:31], v[32:33] op_sel_hi:[1,0]
	v_pk_mul_f32 v[32:33], v[28:29], v[32:33] op_sel_hi:[1,0]
	s_cbranch_execnz .LBB0_1630

.LBB0_1669:
	v_ashrrev_i32_e32 v5, 31, v4
	v_lshl_add_u64 v[10:11], v[4:5], 4, s[6:7]
	global_load_dwordx4 v[6:9], v[10:11], off nt
	s_nop 0
	global_load_dwordx4 v[10:13], v[10:11], off offset:16 nt
	v_add_u32_e32 v0, s2, v0
	v_cmp_lt_i32_e32 vcc, s28, v0
	v_add_u32_e32 v4, s3, v4
	s_or_b64 s[10:11], vcc, s[10:11]
	s_waitcnt vmcnt(0) lgkmcnt(0)
	v_cvt_pk_bf16_f32 v6, v6, v7
	v_cvt_pk_bf16_f32 v7, v8, v9
	v_cvt_pk_bf16_f32 v8, v10, v11
	v_cvt_pk_bf16_f32 v9, v12, v13
	global_store_dwordx4 v[2:3], v[6:9], off
	v_lshl_add_u64 v[2:3], v[2:3], 0, s[0:1]
	s_andn2_b64 exec, exec, s[10:11]
	s_cbranch_execnz .LBB0_1669
